# mLSTM steps 4/5: operand ds_read_b128 renamed onto 5 free quads and issued up to 5 reads ahead with counted lgkmcnt instead of read-wait-mfma through one quad
# speedup vs baseline: 1.0100x; 1.0026x over previous
.LBB0_663:
	ds_read_b32 v182, v140
	s_waitcnt vmcnt(3)
	v_and_b32_e32 v199, 0xffff0000, v78
	v_lshlrev_b32_e32 v198, 16, v78
	s_waitcnt vmcnt(2)
	v_and_b32_e32 v231, 0xffff0000, v74
	v_and_b32_e32 v230, 0xffff0000, v80
	s_waitcnt lgkmcnt(0)
	v_sub_f32_e32 v82, v181, v182
	v_mul_f32_e32 v183, 0x3fb8aa3b, v82
	ds_read_b128 v[82:85], v152
	ds_read_b128 v[86:89], v152 offset:1088
	ds_read_b128 v[90:93], v152 offset:64
	ds_read_b128 v[94:97], v152 offset:1152
	v_readlane_b32 s16, v254, 25
	s_waitcnt lgkmcnt(3)
	v_mfma_f32_16x16x32_bf16 v[82:85], v[82:85], v[78:81], 0
	v_readlane_b32 s17, v254, 26
	v_lshlrev_b64 v[132:133], 10, v[132:133]
	s_mov_b32 s0, 0
	s_waitcnt lgkmcnt(2)
	v_mfma_f32_16x16x32_bf16 v[86:89], v[86:89], v[78:81], 0
	s_waitcnt lgkmcnt(1)
	v_mfma_f32_16x16x32_bf16 v[82:85], v[90:93], v[74:77], v[82:85]
	s_waitcnt lgkmcnt(0)
	v_mfma_f32_16x16x32_bf16 v[86:89], v[94:97], v[74:77], v[86:89]
	ds_read_b128 v[90:93], v152 offset:128
	ds_read_b128 v[94:97], v152 offset:1216
	s_waitcnt vmcnt(1) lgkmcnt(1)
	v_mfma_f32_16x16x32_bf16 v[82:85], v[90:93], v[70:73], v[82:85]
	s_waitcnt lgkmcnt(0)
	v_mfma_f32_16x16x32_bf16 v[86:89], v[94:97], v[70:73], v[86:89]
	ds_read_b128 v[90:93], v152 offset:192
	ds_read_b128 v[94:97], v152 offset:1280
	s_waitcnt vmcnt(0) lgkmcnt(1)
	v_mfma_f32_16x16x32_bf16 v[82:85], v[90:93], v[66:69], v[82:85]
	s_waitcnt lgkmcnt(0)
	v_mfma_f32_16x16x32_bf16 v[86:89], v[94:97], v[66:69], v[86:89]
	ds_read_b128 v[90:93], v142
	ds_read_b128 v[94:97], v142 offset:16
	s_waitcnt lgkmcnt(1)
	v_sub_f32_e32 v90, v90, v182
	v_sub_f32_e32 v91, v91, v182
	v_mul_f32_e32 v90, 0x3fb8aa3b, v90
	v_mul_f32_e32 v91, 0x3fb8aa3b, v91
	v_exp_f32_e32 v90, v90
	v_exp_f32_e32 v91, v91
	v_mul_f32_e32 v82, v82, v90
	v_mul_f32_e32 v83, v83, v91
	v_cndmask_b32_e64 v90, v82, 0, s[24:25]
	s_waitcnt lgkmcnt(0)
	v_sub_f32_e32 v82, v94, v182
	v_cndmask_b32_e64 v91, 0, v83, s[26:27]
	v_sub_f32_e32 v83, v95, v182
	v_mul_f32_e32 v82, 0x3fb8aa3b, v82
	v_mul_f32_e32 v83, 0x3fb8aa3b, v83
	v_exp_f32_e32 v82, v82
	v_exp_f32_e32 v83, v83
	s_nop 0
	v_pk_mul_f32 v[82:83], v[86:87], v[82:83]
	s_nop 0
	v_cndmask_b32_e64 v95, v83, 0, s[28:29]
	v_sub_f32_e32 v83, v96, v182
	v_mul_f32_e32 v83, 0x3fb8aa3b, v83
	v_cndmask_b32_e64 v98, v82, 0, s[30:31]
	v_sub_f32_e32 v82, v92, v182
	v_exp_f32_e32 v86, v83
	v_sub_f32_e32 v83, v93, v182
	v_mul_f32_e32 v82, 0x3fb8aa3b, v82
	v_mul_f32_e32 v83, 0x3fb8aa3b, v83
	v_exp_f32_e32 v82, v82
	v_exp_f32_e32 v83, v83
	s_nop 0
	v_pk_mul_f32 v[82:83], v[84:85], v[82:83]
	s_nop 0
	v_cndmask_b32_e64 v85, v82, 0, s[36:37]
	v_sub_f32_e32 v82, v97, v182
	v_mul_f32_e32 v82, 0x3fb8aa3b, v82
	v_exp_f32_e32 v87, v82
	v_cndmask_b32_e64 v84, v83, 0, s[34:35]
	v_pk_mul_f32 v[82:83], v[88:89], v[86:87]
	s_nop 0
	v_cndmask_b32_e64 v87, v82, 0, s[40:41]
	v_add_f32_e32 v82, 0, v90
	v_add_f32_e32 v82, v91, v82
	v_add_f32_e32 v82, v85, v82
	v_add_f32_e32 v82, v84, v82
	v_add_f32_e32 v82, v98, v82
	v_add_f32_e32 v82, v95, v82
	v_cndmask_b32_e64 v86, v83, 0, s[38:39]
	v_add_f32_e32 v82, v87, v82
	v_add_f32_e32 v94, v86, v82
	v_cvt_pk_bf16_f32 v82, v90, v91
	v_cvt_pk_bf16_f32 v83, v85, v84
	v_cvt_pk_bf16_f32 v85, v87, v86
	ds_read_b128 v[86:89], v152 offset:8704
	ds_read_b128 v[90:93], v152 offset:9792
	v_cvt_pk_bf16_f32 v84, v98, v95
	ds_read_b128 v[96:99], v152 offset:8768
	ds_read_b128 v[184:187], v152 offset:9856
	s_waitcnt lgkmcnt(3)
	v_mfma_f32_16x16x32_bf16 v[86:89], v[86:89], v[78:81], 0
	s_waitcnt lgkmcnt(2)
	v_mfma_f32_16x16x32_bf16 v[90:93], v[90:93], v[78:81], 0
	s_waitcnt lgkmcnt(1)
	v_mfma_f32_16x16x32_bf16 v[86:89], v[96:99], v[74:77], v[86:89]
	s_waitcnt lgkmcnt(0)
	v_mfma_f32_16x16x32_bf16 v[90:93], v[184:187], v[74:77], v[90:93]
	ds_read_b128 v[96:99], v152 offset:8832
	ds_read_b128 v[184:187], v152 offset:9920
	s_waitcnt lgkmcnt(1)
	v_mfma_f32_16x16x32_bf16 v[86:89], v[96:99], v[70:73], v[86:89]
	s_waitcnt lgkmcnt(0)
	v_mfma_f32_16x16x32_bf16 v[96:99], v[184:187], v[70:73], v[90:93]
	s_nop 2
	ds_read_b128 v[90:93], v152 offset:8896
	ds_read_b128 v[184:187], v152 offset:9984
	s_waitcnt lgkmcnt(1)
	v_mfma_f32_16x16x32_bf16 v[90:93], v[90:93], v[66:69], v[86:89]
	s_waitcnt lgkmcnt(0)
	v_mfma_f32_16x16x32_bf16 v[86:89], v[184:187], v[66:69], v[96:99]
	s_nop 2
	ds_read_b128 v[96:99], v142 offset:128
	ds_read_b128 v[184:187], v142 offset:144
	s_waitcnt lgkmcnt(1)
	v_sub_f32_e32 v95, v96, v182
	v_mul_f32_e32 v95, 0x3fb8aa3b, v95
	v_exp_f32_e32 v96, v95
	s_waitcnt lgkmcnt(0)
	v_sub_f32_e32 v95, v184, v182
	v_mul_f32_e32 v95, 0x3fb8aa3b, v95
	v_exp_f32_e32 v100, v95
	v_sub_f32_e32 v95, v97, v182
	v_mul_f32_e32 v95, 0x3fb8aa3b, v95
	v_exp_f32_e32 v97, v95
	s_nop 0
	v_pk_mul_f32 v[90:91], v[90:91], v[96:97]
	s_nop 0
	v_cndmask_b32_e64 v96, v90, 0, s[44:45]
	v_sub_f32_e32 v90, v185, v182
	v_mul_f32_e32 v90, 0x3fb8aa3b, v90
	v_exp_f32_e32 v101, v90
	v_cndmask_b32_e64 v95, v91, 0, s[42:43]
	v_pk_mul_f32 v[86:87], v[86:87], v[100:101]
	s_nop 0
	v_cndmask_b32_e64 v97, v87, 0, s[46:47]
	v_sub_f32_e32 v87, v186, v182
	v_mul_f32_e32 v87, 0x3fb8aa3b, v87
	v_cndmask_b32_e64 v100, v86, 0, s[48:49]
	v_sub_f32_e32 v86, v98, v182
	v_exp_f32_e32 v90, v87
	v_sub_f32_e32 v87, v99, v182
	v_mul_f32_e32 v86, 0x3fb8aa3b, v86
	v_mul_f32_e32 v87, 0x3fb8aa3b, v87
	v_exp_f32_e32 v86, v86
	v_exp_f32_e32 v87, v87
	s_nop 0
	v_pk_mul_f32 v[86:87], v[92:93], v[86:87]
	s_nop 0
	v_cndmask_b32_e64 v93, v86, 0, s[52:53]
	v_sub_f32_e32 v86, v187, v182
	v_mul_f32_e32 v86, 0x3fb8aa3b, v86
	v_exp_f32_e32 v91, v86
	v_cndmask_b32_e64 v92, v87, 0, s[50:51]
	v_pk_mul_f32 v[86:87], v[88:89], v[90:91]
	s_nop 0
	v_cndmask_b32_e64 v90, v86, 0, s[56:57]
	v_add_f32_e32 v86, v94, v96
	v_add_f32_e32 v86, v95, v86
	v_add_f32_e32 v86, v93, v86
	v_add_f32_e32 v86, v92, v86
	v_add_f32_e32 v86, v100, v86
	v_add_f32_e32 v86, v97, v86
	v_cndmask_b32_e64 v89, v87, 0, s[54:55]
	v_add_f32_e32 v86, v90, v86
	v_add_f32_e32 v98, v89, v86
	v_cvt_pk_bf16_f32 v86, v96, v95
	v_cvt_pk_bf16_f32 v87, v93, v92
	v_cvt_pk_bf16_f32 v88, v100, v97
	v_cvt_pk_bf16_f32 v89, v90, v89
	ds_read_b128 v[90:93], v152 offset:17408
	ds_read_b128 v[94:97], v152 offset:18496
	ds_read_b128 v[184:187], v152 offset:17472
	ds_read_b128 v[188:191], v152 offset:18560
	s_waitcnt lgkmcnt(3)
	v_mfma_f32_16x16x32_bf16 v[90:93], v[90:93], v[78:81], 0
	s_waitcnt lgkmcnt(2)
	v_mfma_f32_16x16x32_bf16 v[94:97], v[94:97], v[78:81], 0
	s_waitcnt lgkmcnt(1)
	v_mfma_f32_16x16x32_bf16 v[90:93], v[184:187], v[74:77], v[90:93]
	s_waitcnt lgkmcnt(0)
	v_mfma_f32_16x16x32_bf16 v[94:97], v[188:191], v[74:77], v[94:97]
	ds_read_b128 v[184:187], v152 offset:17536
	ds_read_b128 v[188:191], v152 offset:18624
	s_waitcnt lgkmcnt(1)
	v_mfma_f32_16x16x32_bf16 v[90:93], v[184:187], v[70:73], v[90:93]
	s_waitcnt lgkmcnt(0)
	v_mfma_f32_16x16x32_bf16 v[184:187], v[188:191], v[70:73], v[94:97]
	s_nop 2
	ds_read_b128 v[94:97], v152 offset:17600
	ds_read_b128 v[188:191], v152 offset:18688
	s_waitcnt lgkmcnt(1)
	v_mfma_f32_16x16x32_bf16 v[94:97], v[94:97], v[66:69], v[90:93]
	s_waitcnt lgkmcnt(0)
	v_mfma_f32_16x16x32_bf16 v[90:93], v[188:191], v[66:69], v[184:187]
	s_nop 2
	ds_read_b128 v[184:187], v142 offset:256
	ds_read_b128 v[188:191], v142 offset:272
	s_waitcnt lgkmcnt(1)
	v_sub_f32_e32 v99, v184, v182
	v_mul_f32_e32 v99, 0x3fb8aa3b, v99
	v_exp_f32_e32 v100, v99
	s_waitcnt lgkmcnt(0)
	v_sub_f32_e32 v99, v188, v182
	v_mul_f32_e32 v99, 0x3fb8aa3b, v99
	v_exp_f32_e32 v184, v99
	v_sub_f32_e32 v99, v185, v182
	v_mul_f32_e32 v99, 0x3fb8aa3b, v99
	v_exp_f32_e32 v101, v99
	s_nop 0
	v_pk_mul_f32 v[94:95], v[94:95], v[100:101]
	s_nop 0
	v_cndmask_b32_e64 v100, v94, 0, s[60:61]
	v_sub_f32_e32 v94, v189, v182
	v_mul_f32_e32 v94, 0x3fb8aa3b, v94
	v_exp_f32_e32 v185, v94
	v_cndmask_b32_e64 v99, v95, 0, s[58:59]
	v_pk_mul_f32 v[90:91], v[90:91], v[184:185]
	s_nop 0
	v_cndmask_b32_e64 v101, v91, 0, s[62:63]
	v_sub_f32_e32 v91, v190, v182
	v_mul_f32_e32 v91, 0x3fb8aa3b, v91
	v_cndmask_b32_e64 v172, v90, 0, s[64:65]
	v_sub_f32_e32 v90, v186, v182
	v_exp_f32_e32 v94, v91
	v_sub_f32_e32 v91, v187, v182
	v_mul_f32_e32 v90, 0x3fb8aa3b, v90
	v_mul_f32_e32 v91, 0x3fb8aa3b, v91
	v_exp_f32_e32 v90, v90
	v_exp_f32_e32 v91, v91
	s_nop 0
	v_pk_mul_f32 v[90:91], v[96:97], v[90:91]
	s_nop 0
	v_cndmask_b32_e64 v97, v90, 0, s[68:69]
	v_sub_f32_e32 v90, v191, v182
	v_mul_f32_e32 v90, 0x3fb8aa3b, v90
	v_exp_f32_e32 v95, v90
	v_cndmask_b32_e64 v96, v91, 0, s[66:67]
	v_pk_mul_f32 v[90:91], v[92:93], v[94:95]
	s_nop 0
	v_cndmask_b32_e64 v94, v90, 0, s[72:73]
	v_add_f32_e32 v90, v98, v100
	v_add_f32_e32 v90, v99, v90
	v_add_f32_e32 v90, v97, v90
	v_add_f32_e32 v90, v96, v90
	v_add_f32_e32 v90, v172, v90
	v_add_f32_e32 v90, v101, v90
	v_cndmask_b32_e64 v93, v91, 0, s[70:71]
	v_add_f32_e32 v90, v94, v90
	v_add_f32_e32 v184, v93, v90
	v_cvt_pk_bf16_f32 v90, v100, v99
	v_cvt_pk_bf16_f32 v91, v97, v96
	v_cvt_pk_bf16_f32 v92, v172, v101
	v_cvt_pk_bf16_f32 v93, v94, v93
	ds_read_b128 v[94:97], v152 offset:26112
	ds_read_b128 v[98:101], v152 offset:27200
	ds_read_b128 v[186:189], v152 offset:26176
	ds_read_b128 v[190:193], v152 offset:27264
	s_waitcnt lgkmcnt(3)
	v_mfma_f32_16x16x32_bf16 v[94:97], v[94:97], v[78:81], 0
	s_waitcnt lgkmcnt(2)
	v_mfma_f32_16x16x32_bf16 v[98:101], v[98:101], v[78:81], 0
	s_waitcnt lgkmcnt(1)
	v_mfma_f32_16x16x32_bf16 v[94:97], v[186:189], v[74:77], v[94:97]
	s_waitcnt lgkmcnt(0)
	v_mfma_f32_16x16x32_bf16 v[98:101], v[190:193], v[74:77], v[98:101]
	ds_read_b128 v[186:189], v152 offset:26240
	ds_read_b128 v[190:193], v152 offset:27328
	s_waitcnt lgkmcnt(1)
	v_mfma_f32_16x16x32_bf16 v[94:97], v[186:189], v[70:73], v[94:97]
	s_waitcnt lgkmcnt(0)
	v_mfma_f32_16x16x32_bf16 v[186:189], v[190:193], v[70:73], v[98:101]
	s_nop 2
	ds_read_b128 v[98:101], v152 offset:26304
	ds_read_b128 v[190:193], v152 offset:27392
	s_waitcnt lgkmcnt(1)
	v_mfma_f32_16x16x32_bf16 v[98:101], v[98:101], v[66:69], v[94:97]
	s_waitcnt lgkmcnt(0)
	v_mfma_f32_16x16x32_bf16 v[94:97], v[190:193], v[66:69], v[186:189]
	s_nop 2
	ds_read_b128 v[186:189], v142 offset:384
	ds_read_b128 v[190:193], v142 offset:400
	s_waitcnt lgkmcnt(1)
	v_sub_f32_e32 v172, v186, v182
	v_mul_f32_e32 v172, 0x3fb8aa3b, v172
	v_exp_f32_e32 v186, v172
	s_waitcnt lgkmcnt(0)
	v_sub_f32_e32 v172, v190, v182
	v_mul_f32_e32 v172, 0x3fb8aa3b, v172
	v_exp_f32_e32 v190, v172
	v_sub_f32_e32 v172, v187, v182
	v_mul_f32_e32 v172, 0x3fb8aa3b, v172
	v_exp_f32_e32 v187, v172
	s_nop 0
	v_pk_mul_f32 v[98:99], v[98:99], v[186:187]
	s_nop 0
	v_cndmask_b32_e64 v173, v98, 0, s[76:77]
	v_sub_f32_e32 v98, v191, v182
	v_mul_f32_e32 v98, 0x3fb8aa3b, v98
	v_exp_f32_e32 v191, v98
	v_cndmask_b32_e64 v172, v99, 0, s[74:75]
	v_pk_mul_f32 v[94:95], v[94:95], v[190:191]
	s_nop 0
	v_cndmask_b32_e64 v190, v95, 0, s[78:79]
	v_sub_f32_e32 v95, v192, v182
	v_mul_f32_e32 v95, 0x3fb8aa3b, v95
	v_cndmask_b32_e64 v194, v94, 0, s[80:81]
	v_sub_f32_e32 v94, v188, v182
	v_exp_f32_e32 v98, v95
	v_sub_f32_e32 v95, v189, v182
	v_mul_f32_e32 v94, 0x3fb8aa3b, v94
	v_mul_f32_e32 v95, 0x3fb8aa3b, v95
	v_exp_f32_e32 v94, v94
	v_exp_f32_e32 v95, v95
	s_nop 0
	v_pk_mul_f32 v[94:95], v[100:101], v[94:95]
	s_nop 0
	v_cndmask_b32_e64 v101, v94, 0, s[84:85]
	v_sub_f32_e32 v94, v193, v182
	v_mul_f32_e32 v94, 0x3fb8aa3b, v94
	v_exp_f32_e32 v99, v94
	v_cndmask_b32_e64 v100, v95, 0, s[82:83]
	v_pk_mul_f32 v[94:95], v[96:97], v[98:99]
	s_nop 0
	v_cndmask_b32_e64 v192, v94, 0, s[88:89]
	v_add_f32_e32 v94, v184, v173
	v_add_f32_e32 v94, v172, v94
	v_add_f32_e32 v94, v101, v94
	v_add_u32_e32 v98, 0, v141
	v_add_f32_e32 v196, v100, v94
	v_cvt_pk_bf16_f32 v94, v173, v172
	v_add_u32_e32 v172, 0x22600, v98
	v_cndmask_b32_e64 v188, v95, 0, s[86:87]
	v_cvt_pk_bf16_f32 v95, v101, v100
	ds_read_b128 v[98:101], v172
	ds_read_b128 v[184:187], v172 offset:16
	v_cvt_pk_bf16_f32 v97, v192, v188
	v_cvt_pk_bf16_f32 v96, v194, v190
	s_waitcnt lgkmcnt(1)
	v_pk_mul_f32 v[98:99], v[98:99], v[198:199]
	v_and_b32_e32 v199, 0xffff0000, v79
	v_lshlrev_b32_e32 v198, 16, v79
	v_pk_mul_f32 v[100:101], v[100:101], v[198:199]
	v_add_f32_e32 v98, v98, v99
	v_add_f32_e32 v98, v100, v98
	v_add_f32_e32 v98, v101, v98
	v_add_f32_e32 v173, 0, v98
	ds_read_b128 v[98:101], v172 offset:128
	v_lshlrev_b32_e32 v199, 16, v74
	v_lshlrev_b32_e32 v198, 16, v80
	s_waitcnt lgkmcnt(1)
	v_mov_b32_e32 v200, v184
	v_lshlrev_b32_e32 v184, 16, v81
	s_waitcnt lgkmcnt(0)
	v_mov_b32_e32 v201, v98
	v_mov_b32_e32 v98, v185
	v_pk_mul_f32 v[98:99], v[98:99], v[230:231]
	v_lshlrev_b32_e32 v185, 16, v75
	v_pk_fma_f32 v[98:99], v[200:201], v[198:199], v[98:99]
	v_mov_b32_e32 v198, v186
	v_mov_b32_e32 v199, v100
	v_pk_fma_f32 v[98:99], v[198:199], v[184:185], v[98:99]
	v_and_b32_e32 v185, 0xffff0000, v75
	v_and_b32_e32 v184, 0xffff0000, v81
	v_mov_b32_e32 v100, v187
	v_pk_fma_f32 v[98:99], v[100:101], v[184:185], v[98:99]
	v_and_b32_e32 v231, 0xffff0000, v70
	v_add_f32_e32 v98, v173, v98
	v_add_f32_e32 v173, v98, v99
	ds_read_b128 v[98:101], v172 offset:144
	ds_read_b128 v[184:187], v172 offset:256
	v_and_b32_e32 v230, 0xffff0000, v76
	v_lshlrev_b32_e32 v199, 16, v70
	v_lshlrev_b32_e32 v198, 16, v76
	s_waitcnt lgkmcnt(1)
	v_mov_b32_e32 v200, v98
	s_waitcnt lgkmcnt(0)
	v_mov_b32_e32 v201, v184
	v_mov_b32_e32 v184, v99
	v_pk_mul_f32 v[98:99], v[184:185], v[230:231]
	v_lshlrev_b32_e32 v185, 16, v71
	v_pk_fma_f32 v[98:99], v[200:201], v[198:199], v[98:99]
	v_lshlrev_b32_e32 v184, 16, v77
	v_mov_b32_e32 v198, v100
	v_mov_b32_e32 v199, v186
	v_pk_fma_f32 v[98:99], v[198:199], v[184:185], v[98:99]
	v_and_b32_e32 v185, 0xffff0000, v71
	v_and_b32_e32 v184, 0xffff0000, v77
	v_mov_b32_e32 v186, v101
	v_pk_fma_f32 v[98:99], v[186:187], v[184:185], v[98:99]
	v_and_b32_e32 v231, 0xffff0000, v66
	v_add_f32_e32 v98, v173, v98
	v_add_f32_e32 v173, v98, v99
	ds_read_b128 v[98:101], v172 offset:272
	ds_read_b128 v[184:187], v172 offset:384
	v_and_b32_e32 v230, 0xffff0000, v72
	v_lshlrev_b32_e32 v199, 16, v66
	v_lshlrev_b32_e32 v198, 16, v72
	s_waitcnt lgkmcnt(1)
	v_mov_b32_e32 v200, v98
	s_waitcnt lgkmcnt(0)
	v_mov_b32_e32 v201, v184
	v_mov_b32_e32 v184, v99
	v_pk_mul_f32 v[98:99], v[184:185], v[230:231]
	v_lshlrev_b32_e32 v185, 16, v67
	v_pk_fma_f32 v[98:99], v[200:201], v[198:199], v[98:99]
	v_lshlrev_b32_e32 v184, 16, v73
	v_mov_b32_e32 v198, v100
	v_mov_b32_e32 v199, v186
	v_pk_fma_f32 v[98:99], v[198:199], v[184:185], v[98:99]
	v_and_b32_e32 v185, 0xffff0000, v67
	v_and_b32_e32 v184, 0xffff0000, v73
	v_mov_b32_e32 v186, v101
	v_pk_fma_f32 v[98:99], v[186:187], v[184:185], v[98:99]
	s_load_dwordx2 s[16:17], s[16:17], 0x118
	v_add_f32_e32 v98, v173, v98
	v_add_f32_e32 v189, v98, v99
	ds_read_b128 v[98:101], v172 offset:400
	v_lshlrev_b32_e32 v172, 16, v68
	s_waitcnt lgkmcnt(0)
	v_lshl_add_u64 v[134:135], s[16:17], 0, v[134:135]
	s_mov_b64 s[16:17], 0x2134200
	v_lshl_add_u64 v[134:135], v[134:135], 0, s[16:17]
	v_mul_f32_e32 v195, v98, v172
	v_and_b32_e32 v98, 0xffff0000, v68
	v_mul_f32_e32 v197, v99, v98
	v_lshlrev_b32_e32 v98, 16, v69
	v_mul_f32_e32 v191, v100, v98
	v_and_b32_e32 v98, 0xffff0000, v69
	v_mul_f32_e32 v193, v101, v98
	v_pk_add_f32 v[100:101], v[194:195], v[196:197]
	ds_read_b32 v99, v145
	v_pk_add_f32 v[100:101], v[190:191], v[100:101]
	v_exp_f32_e32 v98, v183
	v_pk_add_f32 v[100:101], v[192:193], v[100:101]
	v_readlane_b32 s16, v254, 60
	v_pk_add_f32 v[100:101], v[188:189], v[100:101]
	ds_bpermute_b32 v184, v143, v100
	ds_bpermute_b32 v185, v143, v101
	ds_read_b128 v[186:189], v169 offset:64
	s_waitcnt lgkmcnt(3)
	v_add_f32_e32 v99, v182, v99
	v_mul_f32_e32 v99, 0xbfb8aa3b, v99
	v_exp_f32_e32 v99, v99
	s_waitcnt lgkmcnt(1)
	v_pk_add_f32 v[100:101], v[100:101], v[184:185]
	ds_bpermute_b32 v184, v144, v100
	ds_bpermute_b32 v185, v144, v101
	v_readlane_b32 s17, v254, 61
	s_waitcnt lgkmcnt(0)
	v_pk_add_f32 v[100:101], v[100:101], v[184:185]
	s_waitcnt lgkmcnt(0)
	ds_read_b128 v[234:237], v169
	ds_read_b128 v[238:241], v169 offset:128
	ds_read_b128 v[242:245], v169 offset:192
	ds_read_b128 v[246:249], v176
	ds_read_b128 v[250:253], v176 offset:64
	s_nop 0
	s_waitcnt lgkmcnt(4)
	v_mfma_f32_16x16x32_bf16 v[182:185], v[234:237], v[78:81], 0
	ds_read_b128 v[234:237], v176 offset:128
	v_fmac_f32_e32 v100, v98, v101
	v_max_f32_e64 v99, |v100|, v99
	v_div_scale_f32 v100, s[90:91], v99, v99, 1.0
	v_mfma_f32_16x16x32_bf16 v[182:185], v[186:189], v[74:77], v[182:185]
	s_nop 0
	v_rcp_f32_e32 v101, v100
	v_lshl_add_u64 v[132:133], s[16:17], 0, v[132:133]
	s_nop 0
	s_waitcnt lgkmcnt(4)
	v_mfma_f32_16x16x32_bf16 v[182:185], v[238:241], v[70:73], v[182:185]
	s_nop 0
	ds_read_b128 v[238:241], v176 offset:192
	v_fma_f32 v172, -v100, v101, 1.0
	v_fmac_f32_e32 v101, v172, v101
	s_nop 0
	s_waitcnt lgkmcnt(4)
	v_mfma_f32_16x16x32_bf16 v[182:185], v[242:245], v[66:69], v[182:185]
	s_nop 0
	ds_read_b128 v[242:245], v169 offset:4416
	v_div_scale_f32 v172, vcc, 1.0, v99, 1.0
	s_nop 5
	v_pk_mul_f32 v[184:185], v[98:99], v[184:185] op_sel_hi:[0,1]
	v_pk_mul_f32 v[182:183], v[98:99], v[182:183] op_sel_hi:[0,1]
	v_mul_f32_e32 v173, v172, v101
	v_fma_f32 v174, -v100, v173, v172
	s_nop 0
	s_waitcnt lgkmcnt(4)
	v_mfma_f32_16x16x32_bf16 v[182:185], v[246:249], v[82:85], v[182:185]
	s_nop 0
	ds_read_b128 v[246:249], v169 offset:4352
	v_fmac_f32_e32 v173, v174, v101
	v_fma_f32 v100, -v100, v173, v172
	s_nop 0
	s_waitcnt lgkmcnt(4)
	v_mfma_f32_16x16x32_bf16 v[182:185], v[250:253], v[86:89], v[182:185]
	s_nop 0
	ds_read_b128 v[250:253], v169 offset:4480
	v_div_fmas_f32 v100, v100, v101, v173
	v_readlane_b32 s90, v254, 19
	s_nop 0
	s_waitcnt lgkmcnt(4)
	v_mfma_f32_16x16x32_bf16 v[182:185], v[234:237], v[90:93], v[182:185]
	s_nop 0
	ds_read_b128 v[234:237], v169 offset:4544
	v_div_fixup_f32 v100, v100, v99, 1.0
	v_cndmask_b32_e64 v133, v133, v135, s[6:7]
	s_nop 0
	s_waitcnt lgkmcnt(4)
	v_mfma_f32_16x16x32_bf16 v[182:185], v[238:241], v[94:97], v[182:185]
	ds_read_b128 v[238:241], v176 offset:4352
	v_cndmask_b32_e64 v132, v132, v134, s[6:7]
	v_readlane_b32 s91, v254, 20
	s_nop 0
	s_nop 4
	v_pk_mul_f32 v[134:135], v[100:101], v[184:185] op_sel_hi:[0,1]
	v_lshl_add_u64 v[132:133], v[132:133], 0, s[90:91]
	v_pk_mul_f32 v[182:183], v[100:101], v[182:183] op_sel_hi:[0,1]
	v_lshl_add_u64 v[132:133], v[132:133], 0, v[0:1]
	v_cvt_pk_bf16_f32 v182, v182, v183
	v_cvt_pk_bf16_f32 v183, v134, v135
	global_store_dwordx2 v[132:133], v[182:183], off
	s_nop 0
	s_nop 0
	s_waitcnt lgkmcnt(3)
	v_mfma_f32_16x16x32_bf16 v[182:185], v[246:249], v[78:81], 0
	ds_read_b128 v[246:249], v176 offset:4416
	v_mfma_f32_16x16x32_bf16 v[182:185], v[242:245], v[74:77], v[182:185]
	s_nop 0
	ds_read_b128 v[242:245], v176 offset:4480
	s_nop 0
	s_waitcnt lgkmcnt(4)
	v_mfma_f32_16x16x32_bf16 v[182:185], v[250:253], v[70:73], v[182:185]
	s_nop 0
	ds_read_b128 v[250:253], v176 offset:4544
	s_nop 0
	s_waitcnt lgkmcnt(4)
	v_mfma_f32_16x16x32_bf16 v[182:185], v[234:237], v[66:69], v[182:185]
	s_nop 0
	ds_read_b128 v[234:237], v169 offset:8768
	s_nop 6
	v_pk_mul_f32 v[184:185], v[98:99], v[184:185] op_sel_hi:[0,1]
	v_pk_mul_f32 v[182:183], v[98:99], v[182:183] op_sel_hi:[0,1]
	s_nop 0
	s_nop 0
	s_waitcnt lgkmcnt(4)
	v_mfma_f32_16x16x32_bf16 v[182:185], v[238:241], v[82:85], v[182:185]
	s_nop 0
	ds_read_b128 v[238:241], v169 offset:8704
	s_nop 0
	s_waitcnt lgkmcnt(4)
	v_mfma_f32_16x16x32_bf16 v[182:185], v[246:249], v[86:89], v[182:185]
	s_nop 0
	ds_read_b128 v[246:249], v169 offset:8832
	s_nop 0
	s_waitcnt lgkmcnt(4)
	v_mfma_f32_16x16x32_bf16 v[182:185], v[242:245], v[90:93], v[182:185]
	s_nop 0
	ds_read_b128 v[242:245], v169 offset:8896
	s_nop 0
	s_waitcnt lgkmcnt(4)
	v_mfma_f32_16x16x32_bf16 v[182:185], v[250:253], v[94:97], v[182:185]
	s_nop 0
	ds_read_b128 v[250:253], v176 offset:8704
	s_nop 6
	v_pk_mul_f32 v[134:135], v[100:101], v[184:185] op_sel_hi:[0,1]
	v_pk_mul_f32 v[182:183], v[100:101], v[182:183] op_sel_hi:[0,1]
	v_cvt_pk_bf16_f32 v182, v182, v183
	v_cvt_pk_bf16_f32 v183, v134, v135
	global_store_dwordx2 v[132:133], v[182:183], off offset:32
	s_nop 0
	s_nop 0
	s_waitcnt lgkmcnt(3)
	v_mfma_f32_16x16x32_bf16 v[182:185], v[238:241], v[78:81], 0
	ds_read_b128 v[238:241], v176 offset:8768
	v_mfma_f32_16x16x32_bf16 v[182:185], v[234:237], v[74:77], v[182:185]
	s_nop 0
	ds_read_b128 v[234:237], v176 offset:8832
	s_nop 0
	s_waitcnt lgkmcnt(4)
	v_mfma_f32_16x16x32_bf16 v[182:185], v[246:249], v[70:73], v[182:185]
	s_nop 0
	ds_read_b128 v[246:249], v176 offset:8896
	s_nop 0
	s_waitcnt lgkmcnt(4)
	v_mfma_f32_16x16x32_bf16 v[182:185], v[242:245], v[66:69], v[182:185]
	s_nop 0
	ds_read_b128 v[242:245], v169 offset:13120
	s_nop 6
	v_pk_mul_f32 v[184:185], v[98:99], v[184:185] op_sel_hi:[0,1]
	v_pk_mul_f32 v[182:183], v[98:99], v[182:183] op_sel_hi:[0,1]
	s_nop 0
	s_nop 0
	s_waitcnt lgkmcnt(4)
	v_mfma_f32_16x16x32_bf16 v[182:185], v[250:253], v[82:85], v[182:185]
	s_nop 0
	ds_read_b128 v[250:253], v169 offset:13056
	s_nop 0
	s_waitcnt lgkmcnt(4)
	v_mfma_f32_16x16x32_bf16 v[182:185], v[238:241], v[86:89], v[182:185]
	s_nop 0
	ds_read_b128 v[238:241], v169 offset:13184
	s_nop 0
	s_waitcnt lgkmcnt(4)
	v_mfma_f32_16x16x32_bf16 v[182:185], v[234:237], v[90:93], v[182:185]
	s_nop 0
	ds_read_b128 v[234:237], v169 offset:13248
	s_nop 0
	s_waitcnt lgkmcnt(4)
	v_mfma_f32_16x16x32_bf16 v[182:185], v[246:249], v[94:97], v[182:185]
	s_nop 0
	ds_read_b128 v[246:249], v176 offset:13056
	s_nop 6
	v_pk_mul_f32 v[134:135], v[100:101], v[184:185] op_sel_hi:[0,1]
	v_pk_mul_f32 v[182:183], v[100:101], v[182:183] op_sel_hi:[0,1]
	v_cvt_pk_bf16_f32 v182, v182, v183
	v_cvt_pk_bf16_f32 v183, v134, v135
	global_store_dwordx2 v[132:133], v[182:183], off offset:64
	s_nop 0
	s_nop 0
	s_waitcnt lgkmcnt(3)
	v_mfma_f32_16x16x32_bf16 v[182:185], v[250:253], v[78:81], 0
	ds_read_b128 v[250:253], v176 offset:13120
	v_mfma_f32_16x16x32_bf16 v[182:185], v[242:245], v[74:77], v[182:185]
	s_nop 0
	ds_read_b128 v[242:245], v176 offset:13184
	s_nop 0
	s_waitcnt lgkmcnt(4)
	v_mfma_f32_16x16x32_bf16 v[182:185], v[238:241], v[70:73], v[182:185]
	s_nop 0
	ds_read_b128 v[238:241], v176 offset:13248
	s_nop 0
	s_waitcnt lgkmcnt(4)
	v_mfma_f32_16x16x32_bf16 v[182:185], v[234:237], v[66:69], v[182:185]
	s_nop 0
	ds_read_b128 v[234:237], v169 offset:17472
	s_nop 6
	v_pk_mul_f32 v[184:185], v[98:99], v[184:185] op_sel_hi:[0,1]
	v_pk_mul_f32 v[182:183], v[98:99], v[182:183] op_sel_hi:[0,1]
	s_nop 0
	s_nop 0
	s_waitcnt lgkmcnt(4)
	v_mfma_f32_16x16x32_bf16 v[182:185], v[246:249], v[82:85], v[182:185]
	s_nop 0
	ds_read_b128 v[246:249], v169 offset:17408
	s_nop 0
	s_waitcnt lgkmcnt(4)
	v_mfma_f32_16x16x32_bf16 v[182:185], v[250:253], v[86:89], v[182:185]
	s_nop 0
	ds_read_b128 v[250:253], v169 offset:17536
	s_nop 0
	s_waitcnt lgkmcnt(4)
	v_mfma_f32_16x16x32_bf16 v[182:185], v[242:245], v[90:93], v[182:185]
	s_nop 0
	ds_read_b128 v[242:245], v169 offset:17600
	s_nop 0
	s_waitcnt lgkmcnt(4)
	v_mfma_f32_16x16x32_bf16 v[182:185], v[238:241], v[94:97], v[182:185]
	s_nop 0
	ds_read_b128 v[238:241], v176 offset:17408
	s_nop 6
	v_pk_mul_f32 v[134:135], v[100:101], v[184:185] op_sel_hi:[0,1]
	v_pk_mul_f32 v[182:183], v[100:101], v[182:183] op_sel_hi:[0,1]
	v_cvt_pk_bf16_f32 v182, v182, v183
	v_cvt_pk_bf16_f32 v183, v134, v135
	global_store_dwordx2 v[132:133], v[182:183], off offset:96
	s_nop 0
	s_nop 0
	s_waitcnt lgkmcnt(3)
	v_mfma_f32_16x16x32_bf16 v[182:185], v[246:249], v[78:81], 0
	ds_read_b128 v[246:249], v176 offset:17472
	v_mfma_f32_16x16x32_bf16 v[182:185], v[234:237], v[74:77], v[182:185]
	s_nop 0
	ds_read_b128 v[234:237], v176 offset:17536
	s_nop 0
	s_waitcnt lgkmcnt(4)
	v_mfma_f32_16x16x32_bf16 v[182:185], v[250:253], v[70:73], v[182:185]
	s_nop 0
	ds_read_b128 v[250:253], v176 offset:17600
	s_nop 0
	s_waitcnt lgkmcnt(4)
	v_mfma_f32_16x16x32_bf16 v[182:185], v[242:245], v[66:69], v[182:185]
	s_nop 0
	ds_read_b128 v[242:245], v169 offset:21824
	s_nop 6
	v_pk_mul_f32 v[184:185], v[98:99], v[184:185] op_sel_hi:[0,1]
	v_pk_mul_f32 v[182:183], v[98:99], v[182:183] op_sel_hi:[0,1]
	s_nop 0
	s_nop 0
	s_waitcnt lgkmcnt(4)
	v_mfma_f32_16x16x32_bf16 v[182:185], v[238:241], v[82:85], v[182:185]
	s_nop 0
	ds_read_b128 v[238:241], v169 offset:21760
	s_nop 0
	s_waitcnt lgkmcnt(4)
	v_mfma_f32_16x16x32_bf16 v[182:185], v[246:249], v[86:89], v[182:185]
	s_nop 0
	ds_read_b128 v[246:249], v169 offset:21888
	s_nop 0
	s_waitcnt lgkmcnt(4)
	v_mfma_f32_16x16x32_bf16 v[182:185], v[234:237], v[90:93], v[182:185]
	s_nop 0
	ds_read_b128 v[234:237], v169 offset:21952
	s_nop 0
	s_waitcnt lgkmcnt(4)
	v_mfma_f32_16x16x32_bf16 v[182:185], v[250:253], v[94:97], v[182:185]
	s_nop 0
	ds_read_b128 v[250:253], v176 offset:21760
	s_nop 6
	v_pk_mul_f32 v[134:135], v[100:101], v[184:185] op_sel_hi:[0,1]
	v_pk_mul_f32 v[182:183], v[100:101], v[182:183] op_sel_hi:[0,1]
	v_cvt_pk_bf16_f32 v182, v182, v183
	v_cvt_pk_bf16_f32 v183, v134, v135
	global_store_dwordx2 v[132:133], v[182:183], off offset:128
	s_nop 0
	s_nop 0
	s_waitcnt lgkmcnt(3)
	v_mfma_f32_16x16x32_bf16 v[182:185], v[238:241], v[78:81], 0
	ds_read_b128 v[238:241], v176 offset:21824
	v_mfma_f32_16x16x32_bf16 v[182:185], v[242:245], v[74:77], v[182:185]
	s_nop 0
	ds_read_b128 v[242:245], v176 offset:21888
	s_nop 0
	s_waitcnt lgkmcnt(4)
	v_mfma_f32_16x16x32_bf16 v[182:185], v[246:249], v[70:73], v[182:185]
	s_nop 0
	ds_read_b128 v[246:249], v176 offset:21952
	s_nop 0
	s_waitcnt lgkmcnt(4)
	v_mfma_f32_16x16x32_bf16 v[182:185], v[234:237], v[66:69], v[182:185]
	s_nop 0
	ds_read_b128 v[234:237], v169 offset:26176
	s_nop 6
	v_pk_mul_f32 v[184:185], v[98:99], v[184:185] op_sel_hi:[0,1]
	v_pk_mul_f32 v[182:183], v[98:99], v[182:183] op_sel_hi:[0,1]
	s_nop 0
	s_nop 0
	s_waitcnt lgkmcnt(4)
	v_mfma_f32_16x16x32_bf16 v[182:185], v[250:253], v[82:85], v[182:185]
	s_nop 0
	ds_read_b128 v[250:253], v169 offset:26112
	s_nop 0
	s_waitcnt lgkmcnt(4)
	v_mfma_f32_16x16x32_bf16 v[182:185], v[238:241], v[86:89], v[182:185]
	s_nop 0
	ds_read_b128 v[238:241], v169 offset:26240
	s_nop 0
	s_waitcnt lgkmcnt(4)
	v_mfma_f32_16x16x32_bf16 v[182:185], v[242:245], v[90:93], v[182:185]
	s_nop 0
	ds_read_b128 v[242:245], v169 offset:26304
	s_nop 0
	s_waitcnt lgkmcnt(4)
	v_mfma_f32_16x16x32_bf16 v[182:185], v[246:249], v[94:97], v[182:185]
	s_nop 0
	ds_read_b128 v[246:249], v176 offset:26112
	s_nop 6
	v_pk_mul_f32 v[134:135], v[100:101], v[184:185] op_sel_hi:[0,1]
	v_pk_mul_f32 v[182:183], v[100:101], v[182:183] op_sel_hi:[0,1]
	v_cvt_pk_bf16_f32 v182, v182, v183
	v_cvt_pk_bf16_f32 v183, v134, v135
	global_store_dwordx2 v[132:133], v[182:183], off offset:160
	s_nop 0
	s_nop 0
	s_waitcnt lgkmcnt(3)
	v_mfma_f32_16x16x32_bf16 v[182:185], v[250:253], v[78:81], 0
	ds_read_b128 v[250:253], v176 offset:26176
	v_mfma_f32_16x16x32_bf16 v[182:185], v[234:237], v[74:77], v[182:185]
	s_nop 0
	ds_read_b128 v[234:237], v176 offset:26240
	s_nop 0
	s_waitcnt lgkmcnt(4)
	v_mfma_f32_16x16x32_bf16 v[182:185], v[238:241], v[70:73], v[182:185]
	s_nop 0
	ds_read_b128 v[238:241], v169 offset:30464
	s_nop 0
	s_waitcnt lgkmcnt(4)
	v_mfma_f32_16x16x32_bf16 v[182:185], v[242:245], v[66:69], v[182:185]
	s_nop 0
	s_nop 6
	v_pk_mul_f32 v[184:185], v[98:99], v[184:185] op_sel_hi:[0,1]
	v_pk_mul_f32 v[182:183], v[98:99], v[182:183] op_sel_hi:[0,1]
	s_nop 0
	s_nop 0
	s_waitcnt lgkmcnt(3)
	v_mfma_f32_16x16x32_bf16 v[182:185], v[246:249], v[82:85], v[182:185]
	s_nop 0
	ds_read_b128 v[242:245], v169 offset:30592
	s_nop 0
	s_waitcnt lgkmcnt(3)
	v_mfma_f32_16x16x32_bf16 v[182:185], v[250:253], v[86:89], v[182:185]
	s_nop 0
	ds_read_b128 v[246:249], v169 offset:30656
	s_nop 0
	s_waitcnt lgkmcnt(3)
	v_mfma_f32_16x16x32_bf16 v[182:185], v[234:237], v[90:93], v[182:185]
	ds_read_b128 v[234:237], v176 offset:30464
	ds_read_b128 v[186:189], v176 offset:26304
	s_nop 0
	s_waitcnt lgkmcnt(0)
	v_mfma_f32_16x16x32_bf16 v[182:185], v[186:189], v[94:97], v[182:185]
	s_nop 7
	v_pk_mul_f32 v[134:135], v[100:101], v[184:185] op_sel_hi:[0,1]
	v_pk_mul_f32 v[182:183], v[100:101], v[182:183] op_sel_hi:[0,1]
	v_cvt_pk_bf16_f32 v182, v182, v183
	v_cvt_pk_bf16_f32 v183, v134, v135
	global_store_dwordx2 v[132:133], v[182:183], off offset:192
	s_nop 0
	ds_read_b128 v[250:253], v176 offset:30528
	s_nop 0
	v_mfma_f32_16x16x32_bf16 v[78:81], v[238:241], v[78:81], 0
	ds_read_b128 v[238:241], v176 offset:30592
	ds_read_b128 v[182:185], v169 offset:30528
	s_nop 0
	s_waitcnt lgkmcnt(0)
	v_mfma_f32_16x16x32_bf16 v[74:77], v[182:185], v[74:77], v[78:81]
	s_nop 4
	s_nop 0
	s_nop 0
	v_mfma_f32_16x16x32_bf16 v[70:73], v[242:245], v[70:73], v[74:77]
	ds_read_b128 v[242:245], v176 offset:30656
	s_nop 2
	s_nop 0
	s_nop 0
	v_mfma_f32_16x16x32_bf16 v[66:69], v[246:249], v[66:69], v[70:73]
	s_nop 2
	s_nop 0
	s_nop 3
	v_pk_mul_f32 v[68:69], v[98:99], v[68:69] op_sel_hi:[0,1]
	v_pk_mul_f32 v[66:67], v[98:99], v[66:67] op_sel_hi:[0,1]
	s_nop 0
	s_nop 0
	v_mfma_f32_16x16x32_bf16 v[66:69], v[234:237], v[82:85], v[66:69]
	s_nop 0
	s_nop 0
	v_mfma_f32_16x16x32_bf16 v[66:69], v[250:253], v[86:89], v[66:69]
	s_nop 0
	s_nop 0
	v_mfma_f32_16x16x32_bf16 v[66:69], v[238:241], v[90:93], v[66:69]
	s_nop 0
	ds_read_b128 v[234:237], v178 offset:34816
	s_nop 0
	s_waitcnt lgkmcnt(1)
	v_mfma_f32_16x16x32_bf16 v[66:69], v[242:245], v[94:97], v[66:69]
	s_nop 7
	v_pk_mul_f32 v[68:69], v[100:101], v[68:69] op_sel_hi:[0,1]
	v_pk_mul_f32 v[66:67], v[100:101], v[66:67] op_sel_hi:[0,1]
	v_cvt_pk_bf16_f32 v66, v66, v67
	v_cvt_pk_bf16_f32 v67, v68, v69
	global_store_dwordx2 v[132:133], v[66:67], off offset:224
	v_sub_f32_e32 v66, v181, v179
	v_mul_f32_e32 v82, 0x3fb8aa3b, v66
	ds_read_b128 v[238:241], v178 offset:34880
	ds_read_b128 v[78:81], v177
	ds_read_b128 v[242:245], v178 offset:34944
	ds_read_b128 v[74:77], v177 offset:64
	ds_read_b128 v[246:249], v178 offset:35008
	ds_read_b128 v[70:73], v177 offset:128
	ds_read_b128 v[250:253], v178 offset:39168
	ds_read_b128 v[66:69], v177 offset:192
	v_exp_f32_e32 v82, v82
	s_nop 0
	v_pk_mul_f32 v[48:49], v[48:49], v[82:83] op_sel_hi:[1,0]
	v_pk_mul_f32 v[46:47], v[46:47], v[82:83] op_sel_hi:[1,0]
	v_pk_mul_f32 v[64:65], v[64:65], v[82:83] op_sel_hi:[1,0]
	v_pk_mul_f32 v[62:63], v[62:63], v[82:83] op_sel_hi:[1,0]
	s_nop 0
	s_waitcnt lgkmcnt(6)
	v_mfma_f32_16x16x32_bf16 v[46:49], v[78:81], v[234:237], v[46:49]
	s_nop 0
	ds_read_b128 v[234:237], v178 offset:39232
	v_pk_mul_f32 v[60:61], v[60:61], v[82:83] op_sel_hi:[1,0]
	v_pk_mul_f32 v[58:59], v[58:59], v[82:83] op_sel_hi:[1,0]
	s_nop 0
	s_waitcnt lgkmcnt(5)
	v_mfma_f32_16x16x32_bf16 v[46:49], v[74:77], v[238:241], v[46:49]
	s_nop 0
	ds_read_b128 v[238:241], v178 offset:39296
	v_pk_mul_f32 v[52:53], v[52:53], v[82:83] op_sel_hi:[1,0]
	v_pk_mul_f32 v[50:51], v[50:51], v[82:83] op_sel_hi:[1,0]
	s_nop 0
	s_waitcnt lgkmcnt(4)
	v_mfma_f32_16x16x32_bf16 v[46:49], v[70:73], v[242:245], v[46:49]
	s_nop 0
	ds_read_b128 v[242:245], v178 offset:39360
	v_pk_mul_f32 v[44:45], v[44:45], v[82:83] op_sel_hi:[1,0]
	v_pk_mul_f32 v[42:43], v[42:43], v[82:83] op_sel_hi:[1,0]
	s_nop 0
	s_waitcnt lgkmcnt(3)
	v_mfma_f32_16x16x32_bf16 v[46:49], v[66:69], v[246:249], v[46:49]
	s_nop 0
	ds_read_b128 v[246:249], v178 offset:43520
	v_pk_mul_f32 v[40:41], v[40:41], v[82:83] op_sel_hi:[1,0]
	v_pk_mul_f32 v[38:39], v[38:39], v[82:83] op_sel_hi:[1,0]
	s_nop 0
	v_mfma_f32_16x16x32_bf16 v[62:65], v[78:81], v[250:253], v[62:65]
	s_nop 0
	ds_read_b128 v[250:253], v178 offset:43584
	v_pk_mul_f32 v[36:37], v[36:37], v[82:83] op_sel_hi:[1,0]
	v_pk_mul_f32 v[34:35], v[34:35], v[82:83] op_sel_hi:[1,0]
	s_nop 0
	s_waitcnt lgkmcnt(4)
	v_mfma_f32_16x16x32_bf16 v[62:65], v[74:77], v[234:237], v[62:65]
	s_nop 0
	ds_read_b128 v[234:237], v178 offset:43648
	v_pk_mul_f32 v[56:57], v[56:57], v[82:83] op_sel_hi:[1,0]
	v_pk_mul_f32 v[54:55], v[54:55], v[82:83] op_sel_hi:[1,0]
	s_nop 0
	s_waitcnt lgkmcnt(4)
	v_mfma_f32_16x16x32_bf16 v[62:65], v[70:73], v[238:241], v[62:65]
	s_nop 0
	ds_read_b128 v[238:241], v178 offset:43712
	s_nop 0
	s_waitcnt lgkmcnt(4)
	v_mfma_f32_16x16x32_bf16 v[62:65], v[66:69], v[242:245], v[62:65]
	s_nop 0
	ds_read_b128 v[242:245], v178 offset:47872
	s_nop 0
	s_waitcnt lgkmcnt(4)
	v_mfma_f32_16x16x32_bf16 v[58:61], v[78:81], v[246:249], v[58:61]
	s_nop 0
	ds_read_b128 v[246:249], v178 offset:47936
	s_nop 0
	s_waitcnt lgkmcnt(4)
	v_mfma_f32_16x16x32_bf16 v[58:61], v[74:77], v[250:253], v[58:61]
	s_nop 0
	ds_read_b128 v[250:253], v178 offset:48000
	s_nop 0
	s_waitcnt lgkmcnt(4)
	v_mfma_f32_16x16x32_bf16 v[58:61], v[70:73], v[234:237], v[58:61]
	s_nop 0
	ds_read_b128 v[234:237], v178 offset:48064
	s_nop 0
	s_waitcnt lgkmcnt(4)
	v_mfma_f32_16x16x32_bf16 v[58:61], v[66:69], v[238:241], v[58:61]
	s_nop 0
	ds_read_b128 v[238:241], v178 offset:52224
	s_nop 0
	s_waitcnt lgkmcnt(4)
	v_mfma_f32_16x16x32_bf16 v[50:53], v[78:81], v[242:245], v[50:53]
	s_nop 0
	ds_read_b128 v[242:245], v178 offset:52288
	s_nop 0
	s_waitcnt lgkmcnt(4)
	v_mfma_f32_16x16x32_bf16 v[50:53], v[74:77], v[246:249], v[50:53]
	s_nop 0
	ds_read_b128 v[246:249], v178 offset:52352
	s_nop 0
	s_waitcnt lgkmcnt(4)
	v_mfma_f32_16x16x32_bf16 v[50:53], v[70:73], v[250:253], v[50:53]
	s_nop 0
	ds_read_b128 v[250:253], v178 offset:52416
	s_nop 0
	s_waitcnt lgkmcnt(4)
	v_mfma_f32_16x16x32_bf16 v[50:53], v[66:69], v[234:237], v[50:53]
	s_nop 0
	ds_read_b128 v[234:237], v178 offset:56576
	s_nop 0
	s_waitcnt lgkmcnt(4)
	v_mfma_f32_16x16x32_bf16 v[42:45], v[78:81], v[238:241], v[42:45]
	s_nop 0
	ds_read_b128 v[238:241], v178 offset:56640
	s_nop 0
	s_waitcnt lgkmcnt(4)
	v_mfma_f32_16x16x32_bf16 v[42:45], v[74:77], v[242:245], v[42:45]
	s_nop 0
	ds_read_b128 v[242:245], v178 offset:56704
	s_nop 0
	s_waitcnt lgkmcnt(4)
	v_mfma_f32_16x16x32_bf16 v[42:45], v[70:73], v[246:249], v[42:45]
	s_nop 0
	ds_read_b128 v[246:249], v178 offset:56768
	s_nop 0
	s_waitcnt lgkmcnt(4)
	v_mfma_f32_16x16x32_bf16 v[42:45], v[66:69], v[250:253], v[42:45]
	s_nop 0
	ds_read_b128 v[250:253], v178 offset:60928
	s_nop 0
	s_waitcnt lgkmcnt(4)
	v_mfma_f32_16x16x32_bf16 v[38:41], v[78:81], v[234:237], v[38:41]
	s_nop 0
	ds_read_b128 v[234:237], v178 offset:60992
	s_nop 0
	s_waitcnt lgkmcnt(4)
	v_mfma_f32_16x16x32_bf16 v[38:41], v[74:77], v[238:241], v[38:41]
	s_nop 0
	ds_read_b128 v[238:241], v178 offset:61056
	s_nop 0
	s_waitcnt lgkmcnt(4)
	v_mfma_f32_16x16x32_bf16 v[38:41], v[70:73], v[242:245], v[38:41]
	s_nop 0
	ds_read_b128 v[242:245], v178 offset:61120
	s_nop 0
	s_waitcnt lgkmcnt(4)
	v_mfma_f32_16x16x32_bf16 v[38:41], v[66:69], v[246:249], v[38:41]
	s_nop 0
	s_nop 0
	s_waitcnt lgkmcnt(3)
	v_mfma_f32_16x16x32_bf16 v[34:37], v[78:81], v[250:253], v[34:37]
	s_nop 0
	s_nop 0
	s_waitcnt lgkmcnt(2)
	v_mfma_f32_16x16x32_bf16 v[34:37], v[74:77], v[234:237], v[34:37]
	s_nop 0
	s_nop 0
	s_waitcnt lgkmcnt(1)
	v_mfma_f32_16x16x32_bf16 v[34:37], v[70:73], v[238:241], v[34:37]
	s_nop 0
	s_nop 0
	s_waitcnt lgkmcnt(0)
	v_mfma_f32_16x16x32_bf16 v[34:37], v[66:69], v[242:245], v[34:37]
	ds_read_b128 v[84:87], v178 offset:65280
	s_nop 0
	s_waitcnt lgkmcnt(0)
	v_mfma_f32_16x16x32_bf16 v[54:57], v[78:81], v[84:87], v[54:57]
	ds_read_b128 v[78:81], v178 offset:65344
	s_nop 0
	s_waitcnt lgkmcnt(0)
	v_mfma_f32_16x16x32_bf16 v[54:57], v[74:77], v[78:81], v[54:57]
	ds_read_b128 v[74:77], v178 offset:65408
	s_nop 0
	s_waitcnt lgkmcnt(0)
	v_mfma_f32_16x16x32_bf16 v[54:57], v[70:73], v[74:77], v[54:57]
	ds_read_b128 v[70:73], v178 offset:65472
	s_nop 0
	s_waitcnt lgkmcnt(0)
	v_mfma_f32_16x16x32_bf16 v[54:57], v[66:69], v[70:73], v[54:57]
	v_lshrrev_b32_e32 v66, 6, v163
	v_and_b32_e32 v67, 15, v163
	v_lshl_add_u32 v66, v66, 4, v67
	v_bfe_u32 v67, v163, 4, 2
	v_mul_u32_u24_e32 v68, 0x110, v66
	v_lshl_add_u32 v67, v67, 4, v68
	v_lshlrev_b32_e32 v66, 2, v66
	v_add_u32_e32 v66, 0x22600, v66
	v_mov_b32_e32 v76, 0x3f803f80
	v_mov_b32_e32 v77, 0x3f803f80
	v_mov_b32_e32 v78, 0x3f803f80
	v_mov_b32_e32 v79, 0x3f803f80
	ds_read_b128 v[68:71], v67 offset:34816
	ds_read_b128 v[72:75], v67 offset:34880
	s_waitcnt lgkmcnt(1)
	v_mfma_f32_16x16x32_bf16 v[84:87], v[76:79], v[68:71], 0
	ds_read_b128 v[68:71], v67 offset:34944
	s_waitcnt lgkmcnt(1)
	v_mfma_f32_16x16x32_bf16 v[84:87], v[76:79], v[72:75], v[84:87]
	ds_read_b128 v[72:75], v67 offset:35008
	ds_read_b32 v67, v66
	s_waitcnt lgkmcnt(2)
	v_mfma_f32_16x16x32_bf16 v[84:87], v[76:79], v[68:71], v[84:87]
	s_waitcnt lgkmcnt(1)
	v_mfma_f32_16x16x32_bf16 v[84:87], v[76:79], v[72:75], v[84:87]
	s_waitcnt lgkmcnt(0)
	s_nop 7
	s_nop 1
	v_fmac_f32_e32 v84, v82, v67

.LBB0_691:
	ds_read_b32 v155, v125
	s_waitcnt vmcnt(3)
	v_and_b32_e32 v187, 0xffff0000, v78
	v_lshlrev_b32_e32 v186, 16, v78
	s_waitcnt vmcnt(2)
	v_and_b32_e32 v191, 0xffff0000, v74
	v_and_b32_e32 v190, 0xffff0000, v80
	s_waitcnt lgkmcnt(0)
	v_sub_f32_e32 v82, v154, v155
	v_mul_f32_e32 v156, 0x3fb8aa3b, v82
	ds_read_b128 v[82:85], v138
	ds_read_b128 v[86:89], v138 offset:1088
	ds_read_b128 v[90:93], v138 offset:64
	ds_read_b128 v[94:97], v138 offset:1152
	v_lshlrev_b64 v[110:111], 10, v[110:111]
	s_waitcnt lgkmcnt(3)
	v_mfma_f32_16x16x32_bf16 v[82:85], v[82:85], v[78:81], 0
	s_mov_b32 s90, 0
	s_waitcnt lgkmcnt(2)
	v_mfma_f32_16x16x32_bf16 v[86:89], v[86:89], v[78:81], 0
	s_waitcnt lgkmcnt(1)
	v_mfma_f32_16x16x32_bf16 v[82:85], v[90:93], v[74:77], v[82:85]
	s_waitcnt lgkmcnt(0)
	v_mfma_f32_16x16x32_bf16 v[86:89], v[94:97], v[74:77], v[86:89]
	ds_read_b128 v[90:93], v138 offset:128
	ds_read_b128 v[94:97], v138 offset:1216
	s_waitcnt vmcnt(1) lgkmcnt(1)
	v_mfma_f32_16x16x32_bf16 v[82:85], v[90:93], v[70:73], v[82:85]
	s_waitcnt lgkmcnt(0)
	v_mfma_f32_16x16x32_bf16 v[86:89], v[94:97], v[70:73], v[86:89]
	ds_read_b128 v[90:93], v138 offset:192
	ds_read_b128 v[94:97], v138 offset:1280
	s_waitcnt vmcnt(0) lgkmcnt(1)
	v_mfma_f32_16x16x32_bf16 v[82:85], v[90:93], v[66:69], v[82:85]
	s_waitcnt lgkmcnt(0)
	v_mfma_f32_16x16x32_bf16 v[86:89], v[94:97], v[66:69], v[86:89]
	ds_read_b128 v[90:93], v127
	ds_read_b128 v[94:97], v127 offset:16
	s_waitcnt lgkmcnt(1)
	v_sub_f32_e32 v90, v90, v155
	v_sub_f32_e32 v91, v91, v155
	v_mul_f32_e32 v90, 0x3fb8aa3b, v90
	v_mul_f32_e32 v91, 0x3fb8aa3b, v91
	v_exp_f32_e32 v90, v90
	v_exp_f32_e32 v91, v91
	v_mul_f32_e32 v82, v82, v90
	v_mul_f32_e32 v83, v83, v91
	v_cndmask_b32_e64 v90, v82, 0, s[24:25]
	s_waitcnt lgkmcnt(0)
	v_sub_f32_e32 v82, v94, v155
	v_cndmask_b32_e64 v91, 0, v83, s[26:27]
	v_sub_f32_e32 v83, v95, v155
	v_mul_f32_e32 v82, 0x3fb8aa3b, v82
	v_mul_f32_e32 v83, 0x3fb8aa3b, v83
	v_exp_f32_e32 v82, v82
	v_exp_f32_e32 v83, v83
	s_nop 0
	v_pk_mul_f32 v[82:83], v[86:87], v[82:83]
	s_nop 0
	v_cndmask_b32_e64 v95, v83, 0, s[28:29]
	v_sub_f32_e32 v83, v96, v155
	v_mul_f32_e32 v83, 0x3fb8aa3b, v83
	v_cndmask_b32_e64 v98, v82, 0, s[30:31]
	v_sub_f32_e32 v82, v92, v155
	v_exp_f32_e32 v86, v83
	v_sub_f32_e32 v83, v93, v155
	v_mul_f32_e32 v82, 0x3fb8aa3b, v82
	v_mul_f32_e32 v83, 0x3fb8aa3b, v83
	v_exp_f32_e32 v82, v82
	v_exp_f32_e32 v83, v83
	s_nop 0
	v_pk_mul_f32 v[82:83], v[84:85], v[82:83]
	s_nop 0
	v_cndmask_b32_e64 v85, v82, 0, s[36:37]
	v_sub_f32_e32 v82, v97, v155
	v_mul_f32_e32 v82, 0x3fb8aa3b, v82
	v_exp_f32_e32 v87, v82
	v_cndmask_b32_e64 v84, v83, 0, s[34:35]
	v_pk_mul_f32 v[82:83], v[88:89], v[86:87]
	s_nop 0
	v_cndmask_b32_e64 v87, v82, 0, s[40:41]
	v_add_f32_e32 v82, 0, v90
	v_add_f32_e32 v82, v91, v82
	v_add_f32_e32 v82, v85, v82
	v_add_f32_e32 v82, v84, v82
	v_add_f32_e32 v82, v98, v82
	v_add_f32_e32 v82, v95, v82
	v_cndmask_b32_e64 v86, v83, 0, s[38:39]
	v_add_f32_e32 v82, v87, v82
	v_add_f32_e32 v94, v86, v82
	v_cvt_pk_bf16_f32 v82, v90, v91
	v_cvt_pk_bf16_f32 v83, v85, v84
	v_cvt_pk_bf16_f32 v85, v87, v86
	ds_read_b128 v[86:89], v138 offset:8704
	ds_read_b128 v[90:93], v138 offset:9792
	v_cvt_pk_bf16_f32 v84, v98, v95
	ds_read_b128 v[96:99], v138 offset:8768
	ds_read_b128 v[158:161], v138 offset:9856
	s_waitcnt lgkmcnt(3)
	v_mfma_f32_16x16x32_bf16 v[86:89], v[86:89], v[78:81], 0
	s_waitcnt lgkmcnt(2)
	v_mfma_f32_16x16x32_bf16 v[90:93], v[90:93], v[78:81], 0
	s_waitcnt lgkmcnt(1)
	v_mfma_f32_16x16x32_bf16 v[86:89], v[96:99], v[74:77], v[86:89]
	s_waitcnt lgkmcnt(0)
	v_mfma_f32_16x16x32_bf16 v[90:93], v[158:161], v[74:77], v[90:93]
	ds_read_b128 v[96:99], v138 offset:8832
	ds_read_b128 v[158:161], v138 offset:9920
	s_waitcnt lgkmcnt(1)
	v_mfma_f32_16x16x32_bf16 v[86:89], v[96:99], v[70:73], v[86:89]
	s_waitcnt lgkmcnt(0)
	v_mfma_f32_16x16x32_bf16 v[96:99], v[158:161], v[70:73], v[90:93]
	s_nop 2
	ds_read_b128 v[90:93], v138 offset:8896
	ds_read_b128 v[158:161], v138 offset:9984
	s_waitcnt lgkmcnt(1)
	v_mfma_f32_16x16x32_bf16 v[90:93], v[90:93], v[66:69], v[86:89]
	s_waitcnt lgkmcnt(0)
	v_mfma_f32_16x16x32_bf16 v[86:89], v[158:161], v[66:69], v[96:99]
	s_nop 2
	ds_read_b128 v[96:99], v127 offset:128
	ds_read_b128 v[158:161], v127 offset:144
	s_waitcnt lgkmcnt(1)
	v_sub_f32_e32 v95, v96, v155
	v_mul_f32_e32 v95, 0x3fb8aa3b, v95
	v_exp_f32_e32 v96, v95
	s_waitcnt lgkmcnt(0)
	v_sub_f32_e32 v95, v158, v155
	v_mul_f32_e32 v95, 0x3fb8aa3b, v95
	v_exp_f32_e32 v100, v95
	v_sub_f32_e32 v95, v97, v155
	v_mul_f32_e32 v95, 0x3fb8aa3b, v95
	v_exp_f32_e32 v97, v95
	s_nop 0
	v_pk_mul_f32 v[90:91], v[90:91], v[96:97]
	s_nop 0
	v_cndmask_b32_e64 v96, v90, 0, s[44:45]
	v_sub_f32_e32 v90, v159, v155
	v_mul_f32_e32 v90, 0x3fb8aa3b, v90
	v_exp_f32_e32 v101, v90
	v_cndmask_b32_e64 v95, v91, 0, s[42:43]
	v_pk_mul_f32 v[86:87], v[86:87], v[100:101]
	s_nop 0
	v_cndmask_b32_e64 v97, v87, 0, s[46:47]
	v_sub_f32_e32 v87, v160, v155
	v_mul_f32_e32 v87, 0x3fb8aa3b, v87
	v_cndmask_b32_e64 v100, v86, 0, s[48:49]
	v_sub_f32_e32 v86, v98, v155
	v_exp_f32_e32 v90, v87
	v_sub_f32_e32 v87, v99, v155
	v_mul_f32_e32 v86, 0x3fb8aa3b, v86
	v_mul_f32_e32 v87, 0x3fb8aa3b, v87
	v_exp_f32_e32 v86, v86
	v_exp_f32_e32 v87, v87
	s_nop 0
	v_pk_mul_f32 v[86:87], v[92:93], v[86:87]
	s_nop 0
	v_cndmask_b32_e64 v93, v86, 0, s[52:53]
	v_sub_f32_e32 v86, v161, v155
	v_mul_f32_e32 v86, 0x3fb8aa3b, v86
	v_exp_f32_e32 v91, v86
	v_cndmask_b32_e64 v92, v87, 0, s[50:51]
	v_pk_mul_f32 v[86:87], v[88:89], v[90:91]
	s_nop 0
	v_cndmask_b32_e64 v90, v86, 0, s[56:57]
	v_add_f32_e32 v86, v94, v96
	v_add_f32_e32 v86, v95, v86
	v_add_f32_e32 v86, v93, v86
	v_add_f32_e32 v86, v92, v86
	v_add_f32_e32 v86, v100, v86
	v_add_f32_e32 v86, v97, v86
	v_cndmask_b32_e64 v89, v87, 0, s[54:55]
	v_add_f32_e32 v86, v90, v86
	v_add_f32_e32 v98, v89, v86
	v_cvt_pk_bf16_f32 v86, v96, v95
	v_cvt_pk_bf16_f32 v87, v93, v92
	v_cvt_pk_bf16_f32 v88, v100, v97
	v_cvt_pk_bf16_f32 v89, v90, v89
	ds_read_b128 v[90:93], v138 offset:17408
	ds_read_b128 v[94:97], v138 offset:18496
	ds_read_b128 v[158:161], v138 offset:17472
	ds_read_b128 v[176:179], v138 offset:18560
	s_waitcnt lgkmcnt(3)
	v_mfma_f32_16x16x32_bf16 v[90:93], v[90:93], v[78:81], 0
	s_waitcnt lgkmcnt(2)
	v_mfma_f32_16x16x32_bf16 v[94:97], v[94:97], v[78:81], 0
	s_waitcnt lgkmcnt(1)
	v_mfma_f32_16x16x32_bf16 v[90:93], v[158:161], v[74:77], v[90:93]
	s_waitcnt lgkmcnt(0)
	v_mfma_f32_16x16x32_bf16 v[94:97], v[176:179], v[74:77], v[94:97]
	ds_read_b128 v[158:161], v138 offset:17536
	ds_read_b128 v[176:179], v138 offset:18624
	s_waitcnt lgkmcnt(1)
	v_mfma_f32_16x16x32_bf16 v[90:93], v[158:161], v[70:73], v[90:93]
	s_waitcnt lgkmcnt(0)
	v_mfma_f32_16x16x32_bf16 v[158:161], v[176:179], v[70:73], v[94:97]
	s_nop 2
	ds_read_b128 v[94:97], v138 offset:17600
	ds_read_b128 v[176:179], v138 offset:18688
	s_waitcnt lgkmcnt(1)
	v_mfma_f32_16x16x32_bf16 v[94:97], v[94:97], v[66:69], v[90:93]
	s_waitcnt lgkmcnt(0)
	v_mfma_f32_16x16x32_bf16 v[90:93], v[176:179], v[66:69], v[158:161]
	s_nop 2
	ds_read_b128 v[158:161], v127 offset:256
	ds_read_b128 v[176:179], v127 offset:272
	s_waitcnt lgkmcnt(1)
	v_sub_f32_e32 v99, v158, v155
	v_mul_f32_e32 v99, 0x3fb8aa3b, v99
	v_exp_f32_e32 v100, v99
	s_waitcnt lgkmcnt(0)
	v_sub_f32_e32 v99, v176, v155
	v_mul_f32_e32 v99, 0x3fb8aa3b, v99
	v_exp_f32_e32 v158, v99
	v_sub_f32_e32 v99, v159, v155
	v_mul_f32_e32 v99, 0x3fb8aa3b, v99
	v_exp_f32_e32 v101, v99
	s_nop 0
	v_pk_mul_f32 v[94:95], v[94:95], v[100:101]
	s_nop 0
	v_cndmask_b32_e64 v100, v94, 0, s[60:61]
	v_sub_f32_e32 v94, v177, v155
	v_mul_f32_e32 v94, 0x3fb8aa3b, v94
	v_exp_f32_e32 v159, v94
	v_cndmask_b32_e64 v99, v95, 0, s[58:59]
	v_pk_mul_f32 v[90:91], v[90:91], v[158:159]
	s_nop 0
	v_cndmask_b32_e64 v101, v91, 0, s[62:63]
	v_sub_f32_e32 v91, v178, v155
	v_mul_f32_e32 v91, 0x3fb8aa3b, v91
	v_cndmask_b32_e64 v158, v90, 0, s[64:65]
	v_sub_f32_e32 v90, v160, v155
	v_exp_f32_e32 v94, v91
	v_sub_f32_e32 v91, v161, v155
	v_mul_f32_e32 v90, 0x3fb8aa3b, v90
	v_mul_f32_e32 v91, 0x3fb8aa3b, v91
	v_exp_f32_e32 v90, v90
	v_exp_f32_e32 v91, v91
	s_nop 0
	v_pk_mul_f32 v[90:91], v[96:97], v[90:91]
	s_nop 0
	v_cndmask_b32_e64 v97, v90, 0, s[68:69]
	v_sub_f32_e32 v90, v179, v155
	v_mul_f32_e32 v90, 0x3fb8aa3b, v90
	v_exp_f32_e32 v95, v90
	v_cndmask_b32_e64 v96, v91, 0, s[66:67]
	v_pk_mul_f32 v[90:91], v[92:93], v[94:95]
	s_nop 0
	v_cndmask_b32_e64 v94, v90, 0, s[72:73]
	v_add_f32_e32 v90, v98, v100
	v_add_f32_e32 v90, v99, v90
	v_add_f32_e32 v90, v97, v90
	v_add_f32_e32 v90, v96, v90
	v_add_f32_e32 v90, v158, v90
	v_add_f32_e32 v90, v101, v90
	v_cndmask_b32_e64 v93, v91, 0, s[70:71]
	v_add_f32_e32 v90, v94, v90
	v_add_f32_e32 v157, v93, v90
	v_cvt_pk_bf16_f32 v90, v100, v99
	v_cvt_pk_bf16_f32 v91, v97, v96
	v_cvt_pk_bf16_f32 v92, v158, v101
	v_cvt_pk_bf16_f32 v93, v94, v93
	ds_read_b128 v[94:97], v138 offset:26112
	ds_read_b128 v[98:101], v138 offset:27200
	ds_read_b128 v[158:161], v138 offset:26176
	ds_read_b128 v[176:179], v138 offset:27264
	s_waitcnt lgkmcnt(3)
	v_mfma_f32_16x16x32_bf16 v[94:97], v[94:97], v[78:81], 0
	s_waitcnt lgkmcnt(2)
	v_mfma_f32_16x16x32_bf16 v[98:101], v[98:101], v[78:81], 0
	s_waitcnt lgkmcnt(1)
	v_mfma_f32_16x16x32_bf16 v[94:97], v[158:161], v[74:77], v[94:97]
	s_waitcnt lgkmcnt(0)
	v_mfma_f32_16x16x32_bf16 v[98:101], v[176:179], v[74:77], v[98:101]
	ds_read_b128 v[158:161], v138 offset:26240
	ds_read_b128 v[176:179], v138 offset:27328
	s_waitcnt lgkmcnt(1)
	v_mfma_f32_16x16x32_bf16 v[94:97], v[158:161], v[70:73], v[94:97]
	s_waitcnt lgkmcnt(0)
	v_mfma_f32_16x16x32_bf16 v[158:161], v[176:179], v[70:73], v[98:101]
	s_nop 2
	ds_read_b128 v[98:101], v138 offset:26304
	ds_read_b128 v[176:179], v138 offset:27392
	s_waitcnt lgkmcnt(1)
	v_mfma_f32_16x16x32_bf16 v[98:101], v[98:101], v[66:69], v[94:97]
	s_waitcnt lgkmcnt(0)
	v_mfma_f32_16x16x32_bf16 v[94:97], v[176:179], v[66:69], v[158:161]
	s_nop 2
	ds_read_b128 v[158:161], v127 offset:384
	ds_read_b128 v[176:179], v127 offset:400
	s_waitcnt lgkmcnt(1)
	v_sub_f32_e32 v158, v158, v155
	v_sub_f32_e32 v159, v159, v155
	v_mul_f32_e32 v158, 0x3fb8aa3b, v158
	v_mul_f32_e32 v159, 0x3fb8aa3b, v159
	v_exp_f32_e32 v158, v158
	v_exp_f32_e32 v159, v159
	s_waitcnt lgkmcnt(0)
	v_sub_f32_e32 v169, v176, v155
	v_mul_f32_e32 v169, 0x3fb8aa3b, v169
	v_exp_f32_e32 v176, v169
	v_pk_mul_f32 v[98:99], v[98:99], v[158:159]
	s_nop 0
	v_cndmask_b32_e64 v159, v98, 0, s[76:77]
	v_sub_f32_e32 v98, v177, v155
	v_mul_f32_e32 v98, 0x3fb8aa3b, v98
	v_exp_f32_e32 v177, v98
	v_cndmask_b32_e64 v158, v99, 0, s[74:75]
	v_pk_mul_f32 v[94:95], v[94:95], v[176:177]
	s_nop 0
	v_cndmask_b32_e64 v176, v95, 0, s[78:79]
	v_sub_f32_e32 v95, v178, v155
	v_mul_f32_e32 v95, 0x3fb8aa3b, v95
	v_cndmask_b32_e64 v180, v94, 0, s[80:81]
	v_sub_f32_e32 v94, v160, v155
	v_exp_f32_e32 v98, v95
	v_sub_f32_e32 v95, v161, v155
	v_mul_f32_e32 v94, 0x3fb8aa3b, v94
	v_mul_f32_e32 v95, 0x3fb8aa3b, v95
	v_exp_f32_e32 v94, v94
	v_exp_f32_e32 v95, v95
	s_nop 0
	v_pk_mul_f32 v[94:95], v[100:101], v[94:95]
	s_nop 0
	v_cndmask_b32_e64 v101, v94, 0, s[84:85]
	v_sub_f32_e32 v94, v179, v155
	v_mul_f32_e32 v94, 0x3fb8aa3b, v94
	v_exp_f32_e32 v99, v94
	v_cndmask_b32_e64 v100, v95, 0, s[82:83]
	v_pk_mul_f32 v[94:95], v[96:97], v[98:99]
	s_nop 0
	v_cndmask_b32_e64 v182, v94, 0, s[88:89]
	v_add_f32_e32 v94, v157, v159
	v_add_f32_e32 v94, v158, v94
	v_add_u32_e32 v98, 0, v126
	v_add_f32_e32 v94, v101, v94
	v_add_u32_e32 v157, 0x22600, v98
	v_cndmask_b32_e64 v178, v95, 0, s[86:87]
	v_add_f32_e32 v184, v100, v94
	v_cvt_pk_bf16_f32 v94, v159, v158
	v_cvt_pk_bf16_f32 v95, v101, v100
	ds_read_b128 v[98:101], v157
	ds_read_b128 v[158:161], v157 offset:16
	v_cvt_pk_bf16_f32 v96, v180, v176
	v_cvt_pk_bf16_f32 v97, v182, v178
	s_waitcnt lgkmcnt(1)
	v_pk_mul_f32 v[98:99], v[98:99], v[186:187]
	v_and_b32_e32 v187, 0xffff0000, v79
	v_lshlrev_b32_e32 v186, 16, v79
	v_pk_mul_f32 v[100:101], v[100:101], v[186:187]
	v_add_f32_e32 v98, v98, v99
	v_add_f32_e32 v98, v100, v98
	v_add_f32_e32 v98, v101, v98
	v_add_f32_e32 v169, 0, v98
	ds_read_b128 v[98:101], v157 offset:128
	v_lshlrev_b32_e32 v187, 16, v74
	v_lshlrev_b32_e32 v186, 16, v80
	s_waitcnt lgkmcnt(1)
	v_mov_b32_e32 v188, v158
	v_lshlrev_b32_e32 v158, 16, v81
	s_waitcnt lgkmcnt(0)
	v_mov_b32_e32 v189, v98
	v_mov_b32_e32 v98, v159
	v_pk_mul_f32 v[98:99], v[98:99], v[190:191]
	v_lshlrev_b32_e32 v159, 16, v75
	v_pk_fma_f32 v[98:99], v[188:189], v[186:187], v[98:99]
	v_mov_b32_e32 v186, v160
	v_mov_b32_e32 v187, v100
	v_pk_fma_f32 v[98:99], v[186:187], v[158:159], v[98:99]
	v_and_b32_e32 v159, 0xffff0000, v75
	v_and_b32_e32 v158, 0xffff0000, v81
	v_mov_b32_e32 v100, v161
	v_pk_fma_f32 v[98:99], v[100:101], v[158:159], v[98:99]
	v_and_b32_e32 v191, 0xffff0000, v70
	v_add_f32_e32 v98, v169, v98
	v_add_f32_e32 v169, v98, v99
	ds_read_b128 v[98:101], v157 offset:144
	ds_read_b128 v[158:161], v157 offset:256
	v_and_b32_e32 v190, 0xffff0000, v76
	v_lshlrev_b32_e32 v187, 16, v70
	v_lshlrev_b32_e32 v186, 16, v76
	s_waitcnt lgkmcnt(1)
	v_mov_b32_e32 v188, v98
	s_waitcnt lgkmcnt(0)
	v_mov_b32_e32 v189, v158
	v_mov_b32_e32 v158, v99
	v_pk_mul_f32 v[98:99], v[158:159], v[190:191]
	v_lshlrev_b32_e32 v159, 16, v71
	v_pk_fma_f32 v[98:99], v[188:189], v[186:187], v[98:99]
	v_lshlrev_b32_e32 v158, 16, v77
	v_mov_b32_e32 v186, v100
	v_mov_b32_e32 v187, v160
	v_pk_fma_f32 v[98:99], v[186:187], v[158:159], v[98:99]
	v_and_b32_e32 v159, 0xffff0000, v71
	v_and_b32_e32 v158, 0xffff0000, v77
	v_mov_b32_e32 v160, v101
	v_pk_fma_f32 v[98:99], v[160:161], v[158:159], v[98:99]
	v_and_b32_e32 v191, 0xffff0000, v66
	v_add_f32_e32 v98, v169, v98
	v_add_f32_e32 v169, v98, v99
	ds_read_b128 v[98:101], v157 offset:272
	ds_read_b128 v[158:161], v157 offset:384
	v_and_b32_e32 v190, 0xffff0000, v72
	v_lshlrev_b32_e32 v187, 16, v66
	v_lshlrev_b32_e32 v186, 16, v72
	s_waitcnt lgkmcnt(1)
	v_mov_b32_e32 v188, v98
	s_waitcnt lgkmcnt(0)
	v_mov_b32_e32 v189, v158
	v_mov_b32_e32 v158, v99
	v_pk_mul_f32 v[98:99], v[158:159], v[190:191]
	v_lshlrev_b32_e32 v159, 16, v67
	v_pk_fma_f32 v[98:99], v[188:189], v[186:187], v[98:99]
	v_lshlrev_b32_e32 v158, 16, v73
	v_mov_b32_e32 v186, v100
	v_mov_b32_e32 v187, v160
	v_pk_fma_f32 v[98:99], v[186:187], v[158:159], v[98:99]
	v_and_b32_e32 v159, 0xffff0000, v67
	v_and_b32_e32 v158, 0xffff0000, v73
	v_mov_b32_e32 v160, v101
	v_pk_fma_f32 v[98:99], v[160:161], v[158:159], v[98:99]
	s_nop 0
	v_add_f32_e32 v98, v169, v98
	v_add_f32_e32 v179, v98, v99
	ds_read_b128 v[98:101], v157 offset:400
	v_lshlrev_b32_e32 v157, 16, v68
	s_waitcnt lgkmcnt(0)
	v_mul_f32_e32 v181, v98, v157
	v_and_b32_e32 v98, 0xffff0000, v68
	v_mul_f32_e32 v185, v99, v98
	v_lshlrev_b32_e32 v98, 16, v69
	v_mul_f32_e32 v177, v100, v98
	v_and_b32_e32 v98, 0xffff0000, v69
	v_mul_f32_e32 v183, v101, v98
	v_pk_add_f32 v[100:101], v[180:181], v[184:185]
	v_exp_f32_e32 v98, v156
	v_pk_add_f32 v[100:101], v[176:177], v[100:101]
	ds_read_b32 v99, v130
	v_pk_add_f32 v[100:101], v[182:183], v[100:101]
	s_nop 0
	v_pk_add_f32 v[100:101], v[178:179], v[100:101]
	ds_bpermute_b32 v156, v128, v100
	ds_bpermute_b32 v157, v128, v101
	ds_read_b128 v[176:179], v148 offset:64
	s_waitcnt lgkmcnt(3)
	v_add_f32_e32 v99, v155, v99
	v_mul_f32_e32 v99, 0xbfb8aa3b, v99
	v_exp_f32_e32 v99, v99
	s_waitcnt lgkmcnt(1)
	v_pk_add_f32 v[100:101], v[100:101], v[156:157]
	ds_bpermute_b32 v156, v129, v100
	ds_bpermute_b32 v157, v129, v101
	s_waitcnt lgkmcnt(0)
	v_pk_add_f32 v[100:101], v[100:101], v[156:157]
	s_nop 0
	v_fmac_f32_e32 v100, v98, v101
	v_max_f32_e64 v99, |v100|, v99
	v_div_scale_f32 v100, s[96:97], v99, v99, 1.0
	v_rcp_f32_e32 v101, v100
	v_readlane_b32 s96, v254, 25
	v_readlane_b32 s97, v254, 26
	s_load_dwordx2 s[96:97], s[96:97], 0x118
	v_fma_f32 v155, -v100, v101, 1.0
	v_fmac_f32_e32 v101, v155, v101
	v_div_scale_f32 v155, vcc, 1.0, v99, 1.0
	v_mul_f32_e32 v156, v155, v101
	v_fma_f32 v157, -v100, v156, v155
	v_fmac_f32_e32 v156, v157, v101
	v_fma_f32 v100, -v100, v156, v155
	v_div_fmas_f32 v100, v100, v101, v156
	s_waitcnt lgkmcnt(0)
	ds_read_b128 v[234:237], v148
	ds_read_b128 v[238:241], v148 offset:128
	ds_read_b128 v[242:245], v148 offset:192
	ds_read_b128 v[246:249], v149
	ds_read_b128 v[250:253], v149 offset:64
	s_nop 0
	s_waitcnt lgkmcnt(4)
	v_mfma_f32_16x16x32_bf16 v[156:159], v[234:237], v[78:81], 0
	ds_read_b128 v[234:237], v149 offset:128
	v_lshl_add_u64 v[112:113], s[96:97], 0, v[112:113]
	s_mov_b64 s[96:97], 0x2134200
	v_lshl_add_u64 v[112:113], v[112:113], 0, s[96:97]
	v_mfma_f32_16x16x32_bf16 v[156:159], v[176:179], v[74:77], v[156:159]
	s_nop 0
	v_readlane_b32 s96, v254, 60
	v_readlane_b32 s97, v254, 61
	s_nop 0
	s_waitcnt lgkmcnt(4)
	v_mfma_f32_16x16x32_bf16 v[156:159], v[238:241], v[70:73], v[156:159]
	s_nop 0
	ds_read_b128 v[238:241], v149 offset:192
	v_lshl_add_u64 v[110:111], s[96:97], 0, v[110:111]
	v_readlane_b32 s96, v254, 19
	s_nop 0
	s_waitcnt lgkmcnt(4)
	v_mfma_f32_16x16x32_bf16 v[156:159], v[242:245], v[66:69], v[156:159]
	s_nop 0
	ds_read_b128 v[242:245], v148 offset:4416
	v_div_fixup_f32 v100, v100, v99, 1.0
	v_cndmask_b32_e64 v111, v111, v113, s[6:7]
	s_nop 4
	v_pk_mul_f32 v[158:159], v[98:99], v[158:159] op_sel_hi:[0,1]
	v_pk_mul_f32 v[156:157], v[98:99], v[156:157] op_sel_hi:[0,1]
	v_cndmask_b32_e64 v110, v110, v112, s[6:7]
	v_readlane_b32 s97, v254, 20
	s_nop 0
	s_waitcnt lgkmcnt(4)
	v_mfma_f32_16x16x32_bf16 v[156:159], v[246:249], v[82:85], v[156:159]
	s_nop 0
	ds_read_b128 v[246:249], v148 offset:4352
	v_lshl_add_u64 v[110:111], v[110:111], 0, s[96:97]
	v_lshl_add_u64 v[110:111], v[110:111], 0, v[0:1]
	s_nop 0
	s_waitcnt lgkmcnt(4)
	v_mfma_f32_16x16x32_bf16 v[156:159], v[250:253], v[86:89], v[156:159]
	s_nop 0
	ds_read_b128 v[250:253], v148 offset:4480
	s_nop 0
	s_waitcnt lgkmcnt(4)
	v_mfma_f32_16x16x32_bf16 v[156:159], v[234:237], v[90:93], v[156:159]
	s_nop 0
	ds_read_b128 v[234:237], v148 offset:4544
	s_nop 0
	s_waitcnt lgkmcnt(4)
	v_mfma_f32_16x16x32_bf16 v[156:159], v[238:241], v[94:97], v[156:159]
	s_nop 0
	ds_read_b128 v[238:241], v149 offset:4352
	s_nop 6
	v_pk_mul_f32 v[112:113], v[100:101], v[158:159] op_sel_hi:[0,1]
	v_pk_mul_f32 v[156:157], v[100:101], v[156:157] op_sel_hi:[0,1]
	v_cvt_pk_bf16_f32 v156, v156, v157
	v_cvt_pk_bf16_f32 v157, v112, v113
	global_store_dwordx2 v[110:111], v[156:157], off
	s_nop 0
	s_nop 0
	s_waitcnt lgkmcnt(3)
	v_mfma_f32_16x16x32_bf16 v[156:159], v[246:249], v[78:81], 0
	ds_read_b128 v[246:249], v149 offset:4416
	v_mfma_f32_16x16x32_bf16 v[156:159], v[242:245], v[74:77], v[156:159]
	s_nop 0
	ds_read_b128 v[242:245], v149 offset:4480
	s_nop 0
	s_waitcnt lgkmcnt(4)
	v_mfma_f32_16x16x32_bf16 v[156:159], v[250:253], v[70:73], v[156:159]
	s_nop 0
	ds_read_b128 v[250:253], v149 offset:4544
	s_nop 0
	s_waitcnt lgkmcnt(4)
	v_mfma_f32_16x16x32_bf16 v[156:159], v[234:237], v[66:69], v[156:159]
	s_nop 0
	ds_read_b128 v[234:237], v148 offset:8768
	s_nop 6
	v_pk_mul_f32 v[158:159], v[98:99], v[158:159] op_sel_hi:[0,1]
	v_pk_mul_f32 v[156:157], v[98:99], v[156:157] op_sel_hi:[0,1]
	s_nop 0
	s_nop 0
	s_waitcnt lgkmcnt(4)
	v_mfma_f32_16x16x32_bf16 v[156:159], v[238:241], v[82:85], v[156:159]
	s_nop 0
	ds_read_b128 v[238:241], v148 offset:8704
	s_nop 0
	s_waitcnt lgkmcnt(4)
	v_mfma_f32_16x16x32_bf16 v[156:159], v[246:249], v[86:89], v[156:159]
	s_nop 0
	ds_read_b128 v[246:249], v148 offset:8832
	s_nop 0
	s_waitcnt lgkmcnt(4)
	v_mfma_f32_16x16x32_bf16 v[156:159], v[242:245], v[90:93], v[156:159]
	s_nop 0
	ds_read_b128 v[242:245], v148 offset:8896
	s_nop 0
	s_waitcnt lgkmcnt(4)
	v_mfma_f32_16x16x32_bf16 v[156:159], v[250:253], v[94:97], v[156:159]
	s_nop 0
	ds_read_b128 v[250:253], v149 offset:8704
	s_nop 6
	v_pk_mul_f32 v[112:113], v[100:101], v[158:159] op_sel_hi:[0,1]
	v_pk_mul_f32 v[156:157], v[100:101], v[156:157] op_sel_hi:[0,1]
	v_cvt_pk_bf16_f32 v156, v156, v157
	v_cvt_pk_bf16_f32 v157, v112, v113
	global_store_dwordx2 v[110:111], v[156:157], off offset:32
	s_nop 0
	s_nop 0
	s_waitcnt lgkmcnt(3)
	v_mfma_f32_16x16x32_bf16 v[156:159], v[238:241], v[78:81], 0
	ds_read_b128 v[238:241], v149 offset:8768
	v_mfma_f32_16x16x32_bf16 v[156:159], v[234:237], v[74:77], v[156:159]
	s_nop 0
	ds_read_b128 v[234:237], v149 offset:8832
	s_nop 0
	s_waitcnt lgkmcnt(4)
	v_mfma_f32_16x16x32_bf16 v[156:159], v[246:249], v[70:73], v[156:159]
	s_nop 0
	ds_read_b128 v[246:249], v149 offset:8896
	s_nop 0
	s_waitcnt lgkmcnt(4)
	v_mfma_f32_16x16x32_bf16 v[156:159], v[242:245], v[66:69], v[156:159]
	s_nop 0
	ds_read_b128 v[242:245], v148 offset:13120
	s_nop 6
	v_pk_mul_f32 v[158:159], v[98:99], v[158:159] op_sel_hi:[0,1]
	v_pk_mul_f32 v[156:157], v[98:99], v[156:157] op_sel_hi:[0,1]
	s_nop 0
	s_nop 0
	s_waitcnt lgkmcnt(4)
	v_mfma_f32_16x16x32_bf16 v[156:159], v[250:253], v[82:85], v[156:159]
	s_nop 0
	ds_read_b128 v[250:253], v148 offset:13056
	s_nop 0
	s_waitcnt lgkmcnt(4)
	v_mfma_f32_16x16x32_bf16 v[156:159], v[238:241], v[86:89], v[156:159]
	s_nop 0
	ds_read_b128 v[238:241], v148 offset:13184
	s_nop 0
	s_waitcnt lgkmcnt(4)
	v_mfma_f32_16x16x32_bf16 v[156:159], v[234:237], v[90:93], v[156:159]
	s_nop 0
	ds_read_b128 v[234:237], v148 offset:13248
	s_nop 0
	s_waitcnt lgkmcnt(4)
	v_mfma_f32_16x16x32_bf16 v[156:159], v[246:249], v[94:97], v[156:159]
	s_nop 0
	ds_read_b128 v[246:249], v149 offset:13056
	s_nop 6
	v_pk_mul_f32 v[112:113], v[100:101], v[158:159] op_sel_hi:[0,1]
	v_pk_mul_f32 v[156:157], v[100:101], v[156:157] op_sel_hi:[0,1]
	v_cvt_pk_bf16_f32 v156, v156, v157
	v_cvt_pk_bf16_f32 v157, v112, v113
	global_store_dwordx2 v[110:111], v[156:157], off offset:64
	s_nop 0
	s_nop 0
	s_waitcnt lgkmcnt(3)
	v_mfma_f32_16x16x32_bf16 v[156:159], v[250:253], v[78:81], 0
	ds_read_b128 v[250:253], v149 offset:13120
	v_mfma_f32_16x16x32_bf16 v[156:159], v[242:245], v[74:77], v[156:159]
	s_nop 0
	ds_read_b128 v[242:245], v149 offset:13184
	s_nop 0
	s_waitcnt lgkmcnt(4)
	v_mfma_f32_16x16x32_bf16 v[156:159], v[238:241], v[70:73], v[156:159]
	s_nop 0
	ds_read_b128 v[238:241], v149 offset:13248
	s_nop 0
	s_waitcnt lgkmcnt(4)
	v_mfma_f32_16x16x32_bf16 v[156:159], v[234:237], v[66:69], v[156:159]
	s_nop 0
	ds_read_b128 v[234:237], v148 offset:17472
	s_nop 6
	v_pk_mul_f32 v[158:159], v[98:99], v[158:159] op_sel_hi:[0,1]
	v_pk_mul_f32 v[156:157], v[98:99], v[156:157] op_sel_hi:[0,1]
	s_nop 0
	s_nop 0
	s_waitcnt lgkmcnt(4)
	v_mfma_f32_16x16x32_bf16 v[156:159], v[246:249], v[82:85], v[156:159]
	s_nop 0
	ds_read_b128 v[246:249], v148 offset:17408
	s_nop 0
	s_waitcnt lgkmcnt(4)
	v_mfma_f32_16x16x32_bf16 v[156:159], v[250:253], v[86:89], v[156:159]
	s_nop 0
	ds_read_b128 v[250:253], v148 offset:17536
	s_nop 0
	s_waitcnt lgkmcnt(4)
	v_mfma_f32_16x16x32_bf16 v[156:159], v[242:245], v[90:93], v[156:159]
	s_nop 0
	ds_read_b128 v[242:245], v148 offset:17600
	s_nop 0
	s_waitcnt lgkmcnt(4)
	v_mfma_f32_16x16x32_bf16 v[156:159], v[238:241], v[94:97], v[156:159]
	s_nop 0
	ds_read_b128 v[238:241], v149 offset:17408
	s_nop 6
	v_pk_mul_f32 v[112:113], v[100:101], v[158:159] op_sel_hi:[0,1]
	v_pk_mul_f32 v[156:157], v[100:101], v[156:157] op_sel_hi:[0,1]
	v_cvt_pk_bf16_f32 v156, v156, v157
	v_cvt_pk_bf16_f32 v157, v112, v113
	global_store_dwordx2 v[110:111], v[156:157], off offset:96
	s_nop 0
	s_nop 0
	s_waitcnt lgkmcnt(3)
	v_mfma_f32_16x16x32_bf16 v[156:159], v[246:249], v[78:81], 0
	ds_read_b128 v[246:249], v149 offset:17472
	v_mfma_f32_16x16x32_bf16 v[156:159], v[234:237], v[74:77], v[156:159]
	s_nop 0
	ds_read_b128 v[234:237], v149 offset:17536
	s_nop 0
	s_waitcnt lgkmcnt(4)
	v_mfma_f32_16x16x32_bf16 v[156:159], v[250:253], v[70:73], v[156:159]
	s_nop 0
	ds_read_b128 v[250:253], v149 offset:17600
	s_nop 0
	s_waitcnt lgkmcnt(4)
	v_mfma_f32_16x16x32_bf16 v[156:159], v[242:245], v[66:69], v[156:159]
	s_nop 0
	ds_read_b128 v[242:245], v148 offset:21824
	s_nop 6
	v_pk_mul_f32 v[158:159], v[98:99], v[158:159] op_sel_hi:[0,1]
	v_pk_mul_f32 v[156:157], v[98:99], v[156:157] op_sel_hi:[0,1]
	s_nop 0
	s_nop 0
	s_waitcnt lgkmcnt(4)
	v_mfma_f32_16x16x32_bf16 v[156:159], v[238:241], v[82:85], v[156:159]
	s_nop 0
	ds_read_b128 v[238:241], v148 offset:21760
	s_nop 0
	s_waitcnt lgkmcnt(4)
	v_mfma_f32_16x16x32_bf16 v[156:159], v[246:249], v[86:89], v[156:159]
	s_nop 0
	ds_read_b128 v[246:249], v148 offset:21888
	s_nop 0
	s_waitcnt lgkmcnt(4)
	v_mfma_f32_16x16x32_bf16 v[156:159], v[234:237], v[90:93], v[156:159]
	s_nop 0
	ds_read_b128 v[234:237], v148 offset:21952
	s_nop 0
	s_waitcnt lgkmcnt(4)
	v_mfma_f32_16x16x32_bf16 v[156:159], v[250:253], v[94:97], v[156:159]
	s_nop 0
	ds_read_b128 v[250:253], v149 offset:21760
	s_nop 6
	v_pk_mul_f32 v[112:113], v[100:101], v[158:159] op_sel_hi:[0,1]
	v_pk_mul_f32 v[156:157], v[100:101], v[156:157] op_sel_hi:[0,1]
	v_cvt_pk_bf16_f32 v156, v156, v157
	v_cvt_pk_bf16_f32 v157, v112, v113
	global_store_dwordx2 v[110:111], v[156:157], off offset:128
	s_nop 0
	s_nop 0
	s_waitcnt lgkmcnt(3)
	v_mfma_f32_16x16x32_bf16 v[156:159], v[238:241], v[78:81], 0
	ds_read_b128 v[238:241], v149 offset:21824
	v_mfma_f32_16x16x32_bf16 v[156:159], v[242:245], v[74:77], v[156:159]
	s_nop 0
	ds_read_b128 v[242:245], v149 offset:21888
	s_nop 0
	s_waitcnt lgkmcnt(4)
	v_mfma_f32_16x16x32_bf16 v[156:159], v[246:249], v[70:73], v[156:159]
	s_nop 0
	ds_read_b128 v[246:249], v149 offset:21952
	s_nop 0
	s_waitcnt lgkmcnt(4)
	v_mfma_f32_16x16x32_bf16 v[156:159], v[234:237], v[66:69], v[156:159]
	s_nop 0
	ds_read_b128 v[234:237], v148 offset:26176
	s_nop 6
	v_pk_mul_f32 v[158:159], v[98:99], v[158:159] op_sel_hi:[0,1]
	v_pk_mul_f32 v[156:157], v[98:99], v[156:157] op_sel_hi:[0,1]
	s_nop 0
	s_nop 0
	s_waitcnt lgkmcnt(4)
	v_mfma_f32_16x16x32_bf16 v[156:159], v[250:253], v[82:85], v[156:159]
	s_nop 0
	ds_read_b128 v[250:253], v148 offset:26112
	s_nop 0
	s_waitcnt lgkmcnt(4)
	v_mfma_f32_16x16x32_bf16 v[156:159], v[238:241], v[86:89], v[156:159]
	s_nop 0
	ds_read_b128 v[238:241], v148 offset:26240
	s_nop 0
	s_waitcnt lgkmcnt(4)
	v_mfma_f32_16x16x32_bf16 v[156:159], v[242:245], v[90:93], v[156:159]
	s_nop 0
	ds_read_b128 v[242:245], v148 offset:26304
	s_nop 0
	s_waitcnt lgkmcnt(4)
	v_mfma_f32_16x16x32_bf16 v[156:159], v[246:249], v[94:97], v[156:159]
	s_nop 0
	ds_read_b128 v[246:249], v149 offset:26112
	s_nop 6
	v_pk_mul_f32 v[112:113], v[100:101], v[158:159] op_sel_hi:[0,1]
	v_pk_mul_f32 v[156:157], v[100:101], v[156:157] op_sel_hi:[0,1]
	v_cvt_pk_bf16_f32 v156, v156, v157
	v_cvt_pk_bf16_f32 v157, v112, v113
	global_store_dwordx2 v[110:111], v[156:157], off offset:160
	s_nop 0
	s_nop 0
	s_waitcnt lgkmcnt(3)
	v_mfma_f32_16x16x32_bf16 v[156:159], v[250:253], v[78:81], 0
	ds_read_b128 v[250:253], v149 offset:26176
	v_mfma_f32_16x16x32_bf16 v[156:159], v[234:237], v[74:77], v[156:159]
	s_nop 0
	ds_read_b128 v[234:237], v149 offset:26240
	s_nop 0
	s_waitcnt lgkmcnt(4)
	v_mfma_f32_16x16x32_bf16 v[156:159], v[238:241], v[70:73], v[156:159]
	s_nop 0
	ds_read_b128 v[238:241], v148 offset:30464
	s_nop 0
	s_waitcnt lgkmcnt(4)
	v_mfma_f32_16x16x32_bf16 v[156:159], v[242:245], v[66:69], v[156:159]
	s_nop 0
	s_nop 6
	v_pk_mul_f32 v[158:159], v[98:99], v[158:159] op_sel_hi:[0,1]
	v_pk_mul_f32 v[156:157], v[98:99], v[156:157] op_sel_hi:[0,1]
	s_nop 0
	s_nop 0
	s_waitcnt lgkmcnt(3)
	v_mfma_f32_16x16x32_bf16 v[156:159], v[246:249], v[82:85], v[156:159]
	s_nop 0
	ds_read_b128 v[242:245], v148 offset:30592
	s_nop 0
	s_waitcnt lgkmcnt(3)
	v_mfma_f32_16x16x32_bf16 v[156:159], v[250:253], v[86:89], v[156:159]
	s_nop 0
	ds_read_b128 v[246:249], v148 offset:30656
	s_nop 0
	s_waitcnt lgkmcnt(3)
	v_mfma_f32_16x16x32_bf16 v[156:159], v[234:237], v[90:93], v[156:159]
	ds_read_b128 v[234:237], v149 offset:30464
	ds_read_b128 v[176:179], v149 offset:26304
	s_nop 0
	s_waitcnt lgkmcnt(0)
	v_mfma_f32_16x16x32_bf16 v[156:159], v[176:179], v[94:97], v[156:159]
	s_nop 7
	v_pk_mul_f32 v[112:113], v[100:101], v[158:159] op_sel_hi:[0,1]
	v_pk_mul_f32 v[156:157], v[100:101], v[156:157] op_sel_hi:[0,1]
	v_cvt_pk_bf16_f32 v156, v156, v157
	v_cvt_pk_bf16_f32 v157, v112, v113
	global_store_dwordx2 v[110:111], v[156:157], off offset:192
	s_nop 0
	ds_read_b128 v[250:253], v149 offset:30528
	s_nop 0
	v_mfma_f32_16x16x32_bf16 v[78:81], v[238:241], v[78:81], 0
	ds_read_b128 v[238:241], v149 offset:30592
	ds_read_b128 v[156:159], v148 offset:30528
	s_nop 0
	s_waitcnt lgkmcnt(0)
	v_mfma_f32_16x16x32_bf16 v[74:77], v[156:159], v[74:77], v[78:81]
	s_nop 4
	s_nop 0
	s_nop 0
	v_mfma_f32_16x16x32_bf16 v[70:73], v[242:245], v[70:73], v[74:77]
	ds_read_b128 v[242:245], v149 offset:30656
	s_nop 2
	s_nop 0
	s_nop 0
	v_mfma_f32_16x16x32_bf16 v[66:69], v[246:249], v[66:69], v[70:73]
	s_nop 2
	s_nop 0
	s_nop 3
	v_pk_mul_f32 v[68:69], v[98:99], v[68:69] op_sel_hi:[0,1]
	v_pk_mul_f32 v[66:67], v[98:99], v[66:67] op_sel_hi:[0,1]
	s_nop 0
	s_nop 0
	v_mfma_f32_16x16x32_bf16 v[66:69], v[234:237], v[82:85], v[66:69]
	s_nop 0
	s_nop 0
	v_mfma_f32_16x16x32_bf16 v[66:69], v[250:253], v[86:89], v[66:69]
	s_nop 0
	s_nop 0
	v_mfma_f32_16x16x32_bf16 v[66:69], v[238:241], v[90:93], v[66:69]
	s_nop 0
	ds_read_b128 v[234:237], v151 offset:34816
	s_nop 0
	s_waitcnt lgkmcnt(1)
	v_mfma_f32_16x16x32_bf16 v[66:69], v[242:245], v[94:97], v[66:69]
	s_nop 7
	v_pk_mul_f32 v[68:69], v[100:101], v[68:69] op_sel_hi:[0,1]
	v_pk_mul_f32 v[66:67], v[100:101], v[66:67] op_sel_hi:[0,1]
	v_cvt_pk_bf16_f32 v66, v66, v67
	v_cvt_pk_bf16_f32 v67, v68, v69
	global_store_dwordx2 v[110:111], v[66:67], off offset:224
	v_sub_f32_e32 v66, v154, v152
	v_mul_f32_e32 v82, 0x3fb8aa3b, v66
	ds_read_b128 v[238:241], v151 offset:34880
	ds_read_b128 v[78:81], v150
	ds_read_b128 v[242:245], v151 offset:34944
	ds_read_b128 v[74:77], v150 offset:64
	ds_read_b128 v[246:249], v151 offset:35008
	ds_read_b128 v[70:73], v150 offset:128
	ds_read_b128 v[250:253], v151 offset:39168
	ds_read_b128 v[66:69], v150 offset:192
	v_exp_f32_e32 v82, v82
	s_nop 0
	v_pk_mul_f32 v[4:5], v[4:5], v[82:83] op_sel_hi:[1,0]
	v_pk_mul_f32 v[2:3], v[2:3], v[82:83] op_sel_hi:[1,0]
	v_pk_mul_f32 v[8:9], v[8:9], v[82:83] op_sel_hi:[1,0]
	v_pk_mul_f32 v[6:7], v[6:7], v[82:83] op_sel_hi:[1,0]
	s_nop 0
	s_waitcnt lgkmcnt(6)
	v_mfma_f32_16x16x32_bf16 v[2:5], v[78:81], v[234:237], v[2:5]
	s_nop 0
	ds_read_b128 v[234:237], v151 offset:39232
	v_pk_mul_f32 v[12:13], v[12:13], v[82:83] op_sel_hi:[1,0]
	v_pk_mul_f32 v[10:11], v[10:11], v[82:83] op_sel_hi:[1,0]
	s_nop 0
	s_waitcnt lgkmcnt(5)
	v_mfma_f32_16x16x32_bf16 v[2:5], v[74:77], v[238:241], v[2:5]
	s_nop 0
	ds_read_b128 v[238:241], v151 offset:39296
	v_pk_mul_f32 v[16:17], v[16:17], v[82:83] op_sel_hi:[1,0]
	v_pk_mul_f32 v[14:15], v[14:15], v[82:83] op_sel_hi:[1,0]
	s_nop 0
	s_waitcnt lgkmcnt(4)
	v_mfma_f32_16x16x32_bf16 v[2:5], v[70:73], v[242:245], v[2:5]
	s_nop 0
	ds_read_b128 v[242:245], v151 offset:39360
	v_pk_mul_f32 v[20:21], v[20:21], v[82:83] op_sel_hi:[1,0]
	v_pk_mul_f32 v[18:19], v[18:19], v[82:83] op_sel_hi:[1,0]
	s_nop 0
	s_waitcnt lgkmcnt(3)
	v_mfma_f32_16x16x32_bf16 v[2:5], v[66:69], v[246:249], v[2:5]
	s_nop 0
	ds_read_b128 v[246:249], v151 offset:43520
	v_pk_mul_f32 v[24:25], v[24:25], v[82:83] op_sel_hi:[1,0]
	v_pk_mul_f32 v[22:23], v[22:23], v[82:83] op_sel_hi:[1,0]
	s_nop 0
	v_mfma_f32_16x16x32_bf16 v[6:9], v[78:81], v[250:253], v[6:9]
	s_nop 0
	ds_read_b128 v[250:253], v151 offset:43584
	v_pk_mul_f32 v[28:29], v[28:29], v[82:83] op_sel_hi:[1,0]
	v_pk_mul_f32 v[26:27], v[26:27], v[82:83] op_sel_hi:[1,0]
	s_nop 0
	s_waitcnt lgkmcnt(4)
	v_mfma_f32_16x16x32_bf16 v[6:9], v[74:77], v[234:237], v[6:9]
	s_nop 0
	ds_read_b128 v[234:237], v151 offset:43648
	v_pk_mul_f32 v[32:33], v[32:33], v[82:83] op_sel_hi:[1,0]
	v_pk_mul_f32 v[30:31], v[30:31], v[82:83] op_sel_hi:[1,0]
	s_nop 0
	s_waitcnt lgkmcnt(4)
	v_mfma_f32_16x16x32_bf16 v[6:9], v[70:73], v[238:241], v[6:9]
	s_nop 0
	ds_read_b128 v[238:241], v151 offset:43712
	s_nop 0
	s_waitcnt lgkmcnt(4)
	v_mfma_f32_16x16x32_bf16 v[6:9], v[66:69], v[242:245], v[6:9]
	s_nop 0
	ds_read_b128 v[242:245], v151 offset:47872
	s_nop 0
	s_waitcnt lgkmcnt(4)
	v_mfma_f32_16x16x32_bf16 v[10:13], v[78:81], v[246:249], v[10:13]
	s_nop 0
	ds_read_b128 v[246:249], v151 offset:47936
	s_nop 0
	s_waitcnt lgkmcnt(4)
	v_mfma_f32_16x16x32_bf16 v[10:13], v[74:77], v[250:253], v[10:13]
	s_nop 0
	ds_read_b128 v[250:253], v151 offset:48000
	s_nop 0
	s_waitcnt lgkmcnt(4)
	v_mfma_f32_16x16x32_bf16 v[10:13], v[70:73], v[234:237], v[10:13]
	s_nop 0
	ds_read_b128 v[234:237], v151 offset:48064
	s_nop 0
	s_waitcnt lgkmcnt(4)
	v_mfma_f32_16x16x32_bf16 v[10:13], v[66:69], v[238:241], v[10:13]
	s_nop 0
	ds_read_b128 v[238:241], v151 offset:52224
	s_nop 0
	s_waitcnt lgkmcnt(4)
	v_mfma_f32_16x16x32_bf16 v[14:17], v[78:81], v[242:245], v[14:17]
	s_nop 0
	ds_read_b128 v[242:245], v151 offset:52288
	s_nop 0
	s_waitcnt lgkmcnt(4)
	v_mfma_f32_16x16x32_bf16 v[14:17], v[74:77], v[246:249], v[14:17]
	s_nop 0
	ds_read_b128 v[246:249], v151 offset:52352
	s_nop 0
	s_waitcnt lgkmcnt(4)
	v_mfma_f32_16x16x32_bf16 v[14:17], v[70:73], v[250:253], v[14:17]
	s_nop 0
	ds_read_b128 v[250:253], v151 offset:52416
	s_nop 0
	s_waitcnt lgkmcnt(4)
	v_mfma_f32_16x16x32_bf16 v[14:17], v[66:69], v[234:237], v[14:17]
	s_nop 0
	ds_read_b128 v[234:237], v151 offset:56576
	s_nop 0
	s_waitcnt lgkmcnt(4)
	v_mfma_f32_16x16x32_bf16 v[18:21], v[78:81], v[238:241], v[18:21]
	s_nop 0
	ds_read_b128 v[238:241], v151 offset:56640
	s_nop 0
	s_waitcnt lgkmcnt(4)
	v_mfma_f32_16x16x32_bf16 v[18:21], v[74:77], v[242:245], v[18:21]
	s_nop 0
	ds_read_b128 v[242:245], v151 offset:56704
	s_nop 0
	s_waitcnt lgkmcnt(4)
	v_mfma_f32_16x16x32_bf16 v[18:21], v[70:73], v[246:249], v[18:21]
	s_nop 0
	ds_read_b128 v[246:249], v151 offset:56768
	s_nop 0
	s_waitcnt lgkmcnt(4)
	v_mfma_f32_16x16x32_bf16 v[18:21], v[66:69], v[250:253], v[18:21]
	s_nop 0
	ds_read_b128 v[250:253], v151 offset:60928
	s_nop 0
	s_waitcnt lgkmcnt(4)
	v_mfma_f32_16x16x32_bf16 v[22:25], v[78:81], v[234:237], v[22:25]
	s_nop 0
	ds_read_b128 v[234:237], v151 offset:60992
	s_nop 0
	s_waitcnt lgkmcnt(4)
	v_mfma_f32_16x16x32_bf16 v[22:25], v[74:77], v[238:241], v[22:25]
	s_nop 0
	ds_read_b128 v[238:241], v151 offset:61056
	s_nop 0
	s_waitcnt lgkmcnt(4)
	v_mfma_f32_16x16x32_bf16 v[22:25], v[70:73], v[242:245], v[22:25]
	s_nop 0
	ds_read_b128 v[242:245], v151 offset:61120
	s_nop 0
	s_waitcnt lgkmcnt(4)
	v_mfma_f32_16x16x32_bf16 v[22:25], v[66:69], v[246:249], v[22:25]
	s_nop 0
	s_nop 0
	s_waitcnt lgkmcnt(3)
	v_mfma_f32_16x16x32_bf16 v[26:29], v[78:81], v[250:253], v[26:29]
	s_nop 0
	s_nop 0
	s_waitcnt lgkmcnt(2)
	v_mfma_f32_16x16x32_bf16 v[26:29], v[74:77], v[234:237], v[26:29]
	s_nop 0
	s_nop 0
	s_waitcnt lgkmcnt(1)
	v_mfma_f32_16x16x32_bf16 v[26:29], v[70:73], v[238:241], v[26:29]
	s_nop 0
	s_nop 0
	s_waitcnt lgkmcnt(0)
	v_mfma_f32_16x16x32_bf16 v[26:29], v[66:69], v[242:245], v[26:29]
	ds_read_b128 v[84:87], v151 offset:65280
	s_nop 0
	s_waitcnt lgkmcnt(0)
	v_mfma_f32_16x16x32_bf16 v[30:33], v[78:81], v[84:87], v[30:33]
	ds_read_b128 v[78:81], v151 offset:65344
	s_nop 0
	s_waitcnt lgkmcnt(0)
	v_mfma_f32_16x16x32_bf16 v[30:33], v[74:77], v[78:81], v[30:33]
	ds_read_b128 v[74:77], v151 offset:65408
	s_nop 0
	s_waitcnt lgkmcnt(0)
	v_mfma_f32_16x16x32_bf16 v[30:33], v[70:73], v[74:77], v[30:33]
	ds_read_b128 v[70:73], v151 offset:65472
	s_nop 0
	s_waitcnt lgkmcnt(0)
	v_mfma_f32_16x16x32_bf16 v[30:33], v[66:69], v[70:73], v[30:33]
	v_lshrrev_b32_e32 v66, 6, v163
	v_and_b32_e32 v67, 15, v163
	v_lshl_add_u32 v66, v66, 4, v67
	v_bfe_u32 v67, v163, 4, 2
	v_mul_u32_u24_e32 v68, 0x110, v66
	v_lshl_add_u32 v67, v67, 4, v68
	v_lshlrev_b32_e32 v66, 2, v66
	v_add_u32_e32 v66, 0x22600, v66
	v_mov_b32_e32 v76, 0x3f803f80
	v_mov_b32_e32 v77, 0x3f803f80
	v_mov_b32_e32 v78, 0x3f803f80
	v_mov_b32_e32 v79, 0x3f803f80
	ds_read_b128 v[68:71], v67 offset:34816
	ds_read_b128 v[72:75], v67 offset:34880
	s_waitcnt lgkmcnt(1)
	v_mfma_f32_16x16x32_bf16 v[84:87], v[76:79], v[68:71], 0
	ds_read_b128 v[68:71], v67 offset:34944
	s_waitcnt lgkmcnt(1)
	v_mfma_f32_16x16x32_bf16 v[84:87], v[76:79], v[72:75], v[84:87]
	ds_read_b128 v[72:75], v67 offset:35008
	ds_read_b32 v67, v66
	s_waitcnt lgkmcnt(2)
	v_mfma_f32_16x16x32_bf16 v[84:87], v[76:79], v[68:71], v[84:87]
	s_waitcnt lgkmcnt(1)
	v_mfma_f32_16x16x32_bf16 v[84:87], v[76:79], v[72:75], v[84:87]
	s_waitcnt lgkmcnt(0)
	s_nop 7
	s_nop 1
	v_fmac_f32_e32 v84, v82, v67
